# v087 + SP3 fragment-read base addresses hoisted to v253/v254, setprio 0/1 pair between MMA groups dropped, duplicate lgkmcnt wait behind the barrier dropped (ten GEMM K-loops)
# baseline (speedup 1.0000x reference)
.LBB0_238:
	s_add_i32 s53, s2, 0x18000
	s_and_b32 s18, s12, 3
	s_add_i32 s54, s53, s15
	s_mov_b64 s[12:13], 0x80
	s_lshl_b32 s19, s14, 13
	s_lshl_b32 s20, s18, 12
	v_lshl_add_u64 v[8:9], v[8:9], 0, s[12:13]
	s_mov_b32 m0, s54
	s_add_i32 s55, s54, 0x2000
	s_add_i32 s56, s49, 0x8000
	s_add_i32 s57, s49, 0xa000
	s_waitcnt vmcnt(2)
	s_barrier
	global_load_lds_dwordx4 v[8:9], off
	v_lshl_add_u64 v[6:7], v[6:7], 0, s[12:13]
	s_mov_b32 m0, s55
	s_add_u32 s16, s30, 0x40080
	global_load_lds_dwordx4 v[6:7], off
	v_lshl_add_u64 v[2:3], v[2:3], 0, s[12:13]
	s_mov_b32 m0, s56
	s_addc_u32 s17, s31, 0
	s_add_i32 s58, s2, 0x1c000
	global_load_lds_dwordx4 v[2:3], off
	v_lshl_add_u64 v[2:3], v[4:5], 0, s[12:13]
	s_mov_b32 m0, s57
	s_add_i32 s59, s58, s15
	global_load_lds_dwordx4 v[2:3], off
	v_lshl_add_u64 v[2:3], s[16:17], 0, v[196:197]
	s_mov_b32 m0, s59
	s_add_i32 s60, s59, 0x2000
	global_load_lds_dwordx4 v[2:3], off
	v_lshl_add_u64 v[2:3], s[16:17], 0, v[200:201]
	s_mov_b32 m0, s60
	s_mov_b64 s[16:17], 0x17600000
	global_load_lds_dwordx4 v[2:3], off
	v_bfe_u32 v3, v10, 4, 2
	v_and_b32_e32 v2, 15, v10
	v_lshlrev_b32_e32 v4, 3, v3
	v_lshlrev_b32_e32 v3, 4, v3
	v_lshl_or_b32 v1, s14, 6, v2
	v_lshl_or_b32 v2, v2, 6, v3
	v_lshlrev_b32_e32 v3, 2, v10
	v_and_b32_e32 v3, 32, v3
	v_bitop3_b32 v5, v2, s19, v3 bitop3:0xde
	v_bitop3_b32 v205, v2, s20, v3 bitop3:0xde
	v_add_u32_e32 v253, s53, v205
	v_add_u32_e32 v254, s58, v205
	v_bfe_i32 v2, v10, 4, 1
	v_lshlrev_b32_e32 v202, 1, v3
	v_and_b32_e32 v206, 24, v2
	v_lshl_add_u64 v[2:3], s[8:9], 0, v[202:203]
	v_lshl_add_u64 v[208:209], v[2:3], 0, s[16:17]
	v_lshrrev_b32_e32 v3, 1, v15
	v_mul_lo_u32 v2, v17, s0
	s_mov_b32 s63, 0x53000
	v_mad_u64_u32 v[2:3], s[16:17], v3, s63, v[2:3]
	v_or_b32_e32 v2, v2, v16
	v_add_lshl_u32 v202, v2, v18, 1
	v_lshrrev_b32_e32 v3, 1, v11
	v_mul_lo_u32 v2, v12, s0
	v_lshl_or_b32 v231, s18, 6, v4
	v_mad_u64_u32 v[2:3], s[18:19], v3, s63, v[2:3]
	s_waitcnt vmcnt(6)
	s_mov_b64 s[16:17], 0x530080
	v_or_b32_e32 v2, v2, v13
	s_cmpk_lt_u32 s3, 0x100
	v_lshl_add_u64 v[210:211], v[202:203], 0, s[16:17]
	v_add_lshl_u32 v202, v2, v14, 1
	s_cselect_b64 s[14:15], -1, 0
	v_and_b32_e32 v204, 8, v10
	s_mov_b32 s34, 0
	v_mov_b32_e32 v207, v203
	s_ashr_i32 s61, s33, 31
	s_ashr_i32 s62, s40, 31
	v_lshl_add_u64 v[212:213], v[202:203], 0, s[16:17]
	v_mov_b64_e32 v[214:215], 0x1518
	v_mov_b64_e32 v[216:217], 0x1517
	s_movk_i32 s64, 0x2a4
	v_add_u32_e32 v232, s1, v205
	v_add_u32_e32 v233, s5, v205
	v_add_u32_e32 v234, s2, v5
	v_mov_b32_e32 v235, 0x7f7f7f7f
	s_movk_i32 s65, 0x163f
	s_movk_i32 s66, 0x1e3f
	s_movk_i32 s67, 0x2640
	s_movk_i32 s68, 0x1800
	s_movk_i32 s69, 0x800
	s_movk_i32 s70, 0x1a00
	s_mov_b32 s71, 0xa600
	s_movk_i32 s72, 0x200
	s_mov_b64 s[16:17], 0x460fe9c0
	s_movk_i32 s73, 0xf7ff
	s_mov_b64 s[18:19], 0x12dfe1c0
	s_mov_b64 s[20:21], 0x151fcfc0
	s_mov_b64 s[22:23], 0x17603240
	s_movk_i32 s74, 0xf00
	v_mov_b32_e32 v236, 0x3c800000
	v_mov_b32_e32 v237, 0xbcb8aa3b
	v_mov_b32_e32 v238, 0x800
	v_mov_b32_e32 v239, 0xa600
	v_mov_b32_e32 v240, 0x200
	s_barrier
	s_branch .LBB0_241

.LBB0_250:
	s_waitcnt lgkmcnt(0)
	s_barrier
	s_setprio 1
	v_mfma_f32_16x16x128_f8f6f4 v[126:129], v[26:33], v[58:65], v[126:129]
	v_mfma_f32_16x16x128_f8f6f4 v[122:125], v[18:25], v[58:65], v[122:125]
	v_mfma_f32_16x16x128_f8f6f4 v[110:113], v[26:33], v[50:57], v[110:113]
	v_mfma_f32_16x16x128_f8f6f4 v[106:109], v[18:25], v[50:57], v[106:109]
	v_mfma_f32_16x16x128_f8f6f4 v[94:97], v[26:33], v[42:49], v[94:97]
	v_mfma_f32_16x16x128_f8f6f4 v[90:93], v[18:25], v[42:49], v[90:93]
	v_mfma_f32_16x16x128_f8f6f4 v[78:81], v[26:33], v[34:41], v[78:81]
	v_mfma_f32_16x16x128_f8f6f4 v[74:77], v[18:25], v[34:41], v[74:77]
	v_mfma_f32_16x16x128_f8f6f4 v[118:121], v[10:17], v[58:65], v[118:121]
	v_mfma_f32_16x16x128_f8f6f4 v[114:117], v[2:9], v[58:65], v[114:117]
	v_mfma_f32_16x16x128_f8f6f4 v[102:105], v[10:17], v[50:57], v[102:105]
	v_mfma_f32_16x16x128_f8f6f4 v[98:101], v[2:9], v[50:57], v[98:101]
	v_mfma_f32_16x16x128_f8f6f4 v[86:89], v[10:17], v[42:49], v[86:89]
	v_mfma_f32_16x16x128_f8f6f4 v[82:85], v[2:9], v[42:49], v[82:85]
	v_mfma_f32_16x16x128_f8f6f4 v[70:73], v[10:17], v[34:41], v[70:73]
	v_mfma_f32_16x16x128_f8f6f4 v[66:69], v[2:9], v[34:41], v[66:69]
	s_setprio 0
	s_barrier
	ds_read_b128 v[2:5], v253
	ds_read_b128 v[6:9], v253 offset:1024
	ds_read_b128 v[10:13], v253 offset:2048
	ds_read_b128 v[14:17], v253 offset:3072
	ds_read_b128 v[18:21], v254
	ds_read_b128 v[22:25], v254 offset:1024
	ds_read_b128 v[26:29], v254 offset:2048
	ds_read_b128 v[30:33], v254 offset:3072
	s_add_u32 s100, s36, 0x530000
	s_addc_u32 s101, s37, 0
	s_mov_b32 m0, s51
	ds_read_b128 v[34:37], v234 offset:32768
	ds_read_b128 v[38:41], v234 offset:33792
	ds_read_b128 v[42:45], v234 offset:34816
	ds_read_b128 v[46:49], v234 offset:35840
	ds_read_b128 v[50:53], v234 offset:36864
	ds_read_b128 v[54:57], v234 offset:37888
	ds_read_b128 v[58:61], v234 offset:38912
	ds_read_b128 v[62:65], v234 offset:39936
	global_load_lds_dwordx4 v194, s[100:101]
	s_mov_b32 m0, s52
	s_nop 0
	global_load_lds_dwordx4 v198, s[100:101]
	s_waitcnt lgkmcnt(0)
	s_barrier
	s_setprio 1
	v_mfma_f32_16x16x128_f8f6f4 v[190:193], v[2:9], v[34:41], v[190:193]
	v_mfma_f32_16x16x128_f8f6f4 v[186:189], v[10:17], v[34:41], v[186:189]
	v_mfma_f32_16x16x128_f8f6f4 v[174:177], v[2:9], v[42:49], v[174:177]
	v_mfma_f32_16x16x128_f8f6f4 v[170:173], v[10:17], v[42:49], v[170:173]
	v_mfma_f32_16x16x128_f8f6f4 v[158:161], v[2:9], v[50:57], v[158:161]
	v_mfma_f32_16x16x128_f8f6f4 v[154:157], v[10:17], v[50:57], v[154:157]
	v_mfma_f32_16x16x128_f8f6f4 v[142:145], v[2:9], v[58:65], v[142:145]
	v_mfma_f32_16x16x128_f8f6f4 v[138:141], v[10:17], v[58:65], v[138:141]
	v_mfma_f32_16x16x128_f8f6f4 v[182:185], v[18:25], v[34:41], v[182:185]
	v_mfma_f32_16x16x128_f8f6f4 v[178:181], v[26:33], v[34:41], v[178:181]
	v_mfma_f32_16x16x128_f8f6f4 v[166:169], v[18:25], v[42:49], v[166:169]
	v_mfma_f32_16x16x128_f8f6f4 v[162:165], v[26:33], v[42:49], v[162:165]
	v_mfma_f32_16x16x128_f8f6f4 v[150:153], v[18:25], v[50:57], v[150:153]
	v_mfma_f32_16x16x128_f8f6f4 v[146:149], v[26:33], v[50:57], v[146:149]
	v_mfma_f32_16x16x128_f8f6f4 v[134:137], v[18:25], v[58:65], v[134:137]
	v_mfma_f32_16x16x128_f8f6f4 v[130:133], v[26:33], v[58:65], v[130:133]
	s_setprio 0
	s_waitcnt vmcnt(8)
	s_barrier
	s_mov_b32 m0, s54
	ds_read_b128 v[34:37], v234 offset:49152
	ds_read_b128 v[38:41], v234 offset:50176
	ds_read_b128 v[42:45], v234 offset:51200
	ds_read_b128 v[46:49], v234 offset:52224
	ds_read_b128 v[50:53], v234 offset:53248
	ds_read_b128 v[54:57], v234 offset:54272
	ds_read_b128 v[58:61], v234 offset:55296
	ds_read_b128 v[62:65], v234 offset:56320
	s_add_u32 s98, s34, 0x80
	s_addc_u32 s99, s35, 0
	global_load_lds_dwordx4 v196, s[98:99]
	s_mov_b32 m0, s55
	s_nop 0
	global_load_lds_dwordx4 v200, s[98:99]
	s_mov_b32 m0, s59
	s_add_u32 s100, s82, 0x80
	s_addc_u32 s101, s83, 0
	global_load_lds_dwordx4 v196, s[100:101]
	s_mov_b32 m0, s60
	s_nop 0
	global_load_lds_dwordx4 v200, s[100:101]
	s_mov_b32 m0, s56
	s_add_u32 s98, s36, 0x80
	s_addc_u32 s99, s37, 0
	global_load_lds_dwordx4 v194, s[98:99]
	s_mov_b32 m0, s57
	s_nop 0
	global_load_lds_dwordx4 v198, s[98:99]
	s_waitcnt lgkmcnt(0)
	s_barrier
	s_setprio 1
	v_mfma_f32_16x16x128_f8f6f4 v[126:129], v[2:9], v[34:41], v[126:129]
	v_mfma_f32_16x16x128_f8f6f4 v[122:125], v[10:17], v[34:41], v[122:125]
	v_mfma_f32_16x16x128_f8f6f4 v[110:113], v[2:9], v[42:49], v[110:113]
	v_mfma_f32_16x16x128_f8f6f4 v[106:109], v[10:17], v[42:49], v[106:109]
	v_mfma_f32_16x16x128_f8f6f4 v[94:97], v[2:9], v[50:57], v[94:97]
	v_mfma_f32_16x16x128_f8f6f4 v[90:93], v[10:17], v[50:57], v[90:93]
	v_mfma_f32_16x16x128_f8f6f4 v[78:81], v[2:9], v[58:65], v[78:81]
	v_mfma_f32_16x16x128_f8f6f4 v[74:77], v[10:17], v[58:65], v[74:77]
	v_mfma_f32_16x16x128_f8f6f4 v[118:121], v[18:25], v[34:41], v[118:121]
	v_mfma_f32_16x16x128_f8f6f4 v[114:117], v[26:33], v[34:41], v[114:117]
	v_mfma_f32_16x16x128_f8f6f4 v[102:105], v[18:25], v[42:49], v[102:105]
	v_mfma_f32_16x16x128_f8f6f4 v[98:101], v[26:33], v[42:49], v[98:101]
	v_mfma_f32_16x16x128_f8f6f4 v[86:89], v[18:25], v[50:57], v[86:89]
	v_mfma_f32_16x16x128_f8f6f4 v[82:85], v[26:33], v[50:57], v[82:85]
	v_mfma_f32_16x16x128_f8f6f4 v[70:73], v[18:25], v[58:65], v[70:73]
	v_mfma_f32_16x16x128_f8f6f4 v[66:69], v[26:33], v[58:65], v[66:69]
	s_setprio 0
	s_waitcnt vmcnt(8)
	s_barrier
	s_add_i32 s80, s80, 2
	s_add_u32 s30, s30, 0x100
	s_addc_u32 s31, s31, 0
	s_cmp_gt_u32 s80, 13
	s_cbranch_scc1 .LBB0_258

.LBB0_254:
	s_add_u32 s34, s6, s30
	s_addc_u32 s35, s7, s31
	s_add_u32 s34, s34, 0x100
	s_addc_u32 s35, s35, 0
	s_add_u32 s81, s78, s30
	s_addc_u32 s82, s79, s31
	s_waitcnt lgkmcnt(0)
	s_cmpk_eq_i32 s30, 0x700
	s_cselect_b32 s37, s27, s35
	s_cselect_b32 s36, s26, s34
	s_cselect_b32 s35, s5, s82
	s_cselect_b32 s34, s25, s81
	s_barrier
	s_setprio 1
	s_waitcnt lgkmcnt(0)
	v_mfma_f32_16x16x128_f8f6f4 v[190:193], v[26:33], v[58:65], v[190:193]
	v_mfma_f32_16x16x128_f8f6f4 v[186:189], v[18:25], v[58:65], v[186:189]
	v_mfma_f32_16x16x128_f8f6f4 v[174:177], v[26:33], v[50:57], v[174:177]
	v_mfma_f32_16x16x128_f8f6f4 v[170:173], v[18:25], v[50:57], v[170:173]
	v_mfma_f32_16x16x128_f8f6f4 v[158:161], v[26:33], v[42:49], v[158:161]
	v_mfma_f32_16x16x128_f8f6f4 v[154:157], v[18:25], v[42:49], v[154:157]
	v_mfma_f32_16x16x128_f8f6f4 v[142:145], v[26:33], v[34:41], v[142:145]
	v_mfma_f32_16x16x128_f8f6f4 v[138:141], v[18:25], v[34:41], v[138:141]
	v_mfma_f32_16x16x128_f8f6f4 v[182:185], v[10:17], v[58:65], v[182:185]
	v_mfma_f32_16x16x128_f8f6f4 v[178:181], v[2:9], v[58:65], v[178:181]
	v_mfma_f32_16x16x128_f8f6f4 v[166:169], v[10:17], v[50:57], v[166:169]
	v_mfma_f32_16x16x128_f8f6f4 v[162:165], v[2:9], v[50:57], v[162:165]
	v_mfma_f32_16x16x128_f8f6f4 v[150:153], v[10:17], v[42:49], v[150:153]
	v_mfma_f32_16x16x128_f8f6f4 v[146:149], v[2:9], v[42:49], v[146:149]
	v_mfma_f32_16x16x128_f8f6f4 v[134:137], v[10:17], v[34:41], v[134:137]
	v_mfma_f32_16x16x128_f8f6f4 v[130:133], v[2:9], v[34:41], v[130:133]
	s_setprio 0
	s_barrier
	s_mov_b32 m0, s45
	s_add_u32 s82, s34, 0x40000
	ds_read_b128 v[58:61], v234 offset:16384
	ds_read_b128 v[62:65], v234 offset:17408
	ds_read_b128 v[50:53], v234 offset:18432
	ds_read_b128 v[54:57], v234 offset:19456
	ds_read_b128 v[42:45], v234 offset:20480
	ds_read_b128 v[46:49], v234 offset:21504
	ds_read_b128 v[34:37], v234 offset:22528
	ds_read_b128 v[38:41], v234 offset:23552
	global_load_lds_dwordx4 v196, s[34:35]
	s_mov_b32 m0, s46
	s_addc_u32 s83, s35, 0
	global_load_lds_dwordx4 v200, s[34:35]
	s_mov_b32 m0, s47
	s_nop 0
	global_load_lds_dwordx4 v196, s[82:83]
	s_mov_b32 m0, s48
	s_andn2_b64 vcc, exec, s[38:39]
	global_load_lds_dwordx4 v200, s[82:83]
	s_mov_b32 m0, s49
	s_nop 0
	global_load_lds_dwordx4 v194, s[36:37]
	s_mov_b32 m0, s50
	s_nop 0
	global_load_lds_dwordx4 v198, s[36:37]
	s_cbranch_vccnz .LBB0_257
	s_waitcnt vmcnt(16)
	s_cbranch_execnz .LBB0_250
	s_branch .LBB0_249

.LBB0_873:
	s_add_u32 s44, s12, 0x17600000
	s_addc_u32 s45, s13, 0
	s_add_u32 s10, s12, 0xe600000
	s_addc_u32 s11, s13, 0
	s_add_u32 s46, s12, 0x17606480
	s_addc_u32 s47, s13, 0
	s_add_u32 s12, s12, 0x12e00000
	s_addc_u32 s13, s13, 0
	s_lshl_b32 s14, s14, 5
	s_add_i32 s48, s2, 0x18000
	s_and_b32 s23, s14, 0x60
	s_add_i32 s49, s48, s18
	s_mov_b64 s[14:15], 0x80
	s_lshl_b32 s19, s0, 13
	s_lshl_b32 s26, s23, 7
	v_lshl_add_u64 v[8:9], v[8:9], 0, s[14:15]
	s_mov_b32 m0, s49
	s_add_i32 s50, s49, 0x2000
	s_add_i32 s51, s40, 0x8000
	s_add_i32 s52, s40, 0xa000
	s_waitcnt vmcnt(2)
	s_barrier
	global_load_lds_dwordx4 v[8:9], off
	v_lshl_add_u64 v[6:7], v[6:7], 0, s[14:15]
	s_mov_b32 m0, s50
	s_mov_b64 s[16:17], 0x100
	s_add_u32 s24, s6, 0x40080
	global_load_lds_dwordx4 v[6:7], off
	v_lshl_add_u64 v[2:3], v[2:3], 0, s[16:17]
	s_mov_b32 m0, s51
	s_addc_u32 s25, s7, 0
	s_add_i32 s53, s2, 0x1c000
	global_load_lds_dwordx4 v[2:3], off
	v_lshl_add_u64 v[2:3], v[4:5], 0, s[16:17]
	s_mov_b32 m0, s52
	s_add_i32 s54, s53, s18
	global_load_lds_dwordx4 v[2:3], off
	v_lshl_add_u64 v[2:3], s[24:25], 0, v[196:197]
	s_mov_b32 m0, s54
	s_add_i32 s55, s54, 0x2000
	global_load_lds_dwordx4 v[2:3], off
	v_lshl_add_u64 v[2:3], s[24:25], 0, v[200:201]
	s_mov_b32 m0, s55
	s_cmpk_lt_u32 s3, 0x100
	global_load_lds_dwordx4 v[2:3], off
	v_lshrrev_b32_e32 v3, 1, v10
	v_and_b32_e32 v3, 24, v3
	v_and_b32_e32 v2, 15, v10
	v_lshlrev_b32_e32 v4, 1, v3
	v_lshl_or_b32 v1, s0, 6, v2
	v_lshl_or_b32 v2, v2, 6, v4
	v_lshlrev_b32_e32 v4, 2, v10
	v_and_b32_e32 v4, 32, v4
	v_bitop3_b32 v5, v2, s19, v4 bitop3:0xde
	v_bitop3_b32 v222, v2, s26, v4 bitop3:0xde
	v_add_u32_e32 v253, s48, v222
	v_add_u32_e32 v254, s53, v222
	v_or_b32_e32 v223, s23, v3
	v_lshrrev_b32_e32 v3, 1, v15
	v_mul_lo_u32 v2, v17, s1
	s_mov_b32 s0, 0x53000
	v_mad_u64_u32 v[2:3], s[24:25], v3, s0, v[2:3]
	v_or_b32_e32 v2, v2, v16
	v_add_lshl_u32 v2, v2, v18, 1
	v_mov_b32_e32 v3, v197
	s_mov_b64 s[24:25], 0x530100
	v_lshl_add_u64 v[202:203], v[2:3], 0, s[24:25]
	v_lshrrev_b32_e32 v3, 1, v11
	v_mul_lo_u32 v2, v12, s1
	v_mad_u64_u32 v[2:3], s[0:1], v3, s0, v[2:3]
	s_waitcnt vmcnt(6)
	v_or_b32_e32 v2, v2, v13
	v_add_lshl_u32 v2, v2, v14, 1
	v_mov_b32_e32 v3, v197
	s_cselect_b64 s[18:19], -1, 0
	s_ashr_i32 s56, s33, 31
	v_lshl_add_u64 v[204:205], v[2:3], 0, s[24:25]
	s_mov_b32 s63, 0
	v_mov_b64_e32 v[206:207], 0x240
	v_mov_b64_e32 v[208:209], 0x23f
	s_movk_i32 s57, 0x49
	v_add_u32_e32 v224, s20, v222
	v_add_u32_e32 v225, s22, v222
	v_add_u32_e32 v226, s2, v5
	v_mov_b32_e32 v227, 0x7f7f7f7f
	s_mov_b32 s58, 0xa600
	s_mov_b32 s20, 0x3a800000
	s_mov_b32 s26, 0
	s_barrier
	s_branch .LBB0_876

.LBB0_885:
	s_waitcnt lgkmcnt(0)
	s_barrier
	s_setprio 1
	v_mfma_f32_16x16x128_f8f6f4 v[126:129], v[26:33], v[58:65], v[126:129]
	v_mfma_f32_16x16x128_f8f6f4 v[122:125], v[18:25], v[58:65], v[122:125]
	v_mfma_f32_16x16x128_f8f6f4 v[110:113], v[26:33], v[50:57], v[110:113]
	v_mfma_f32_16x16x128_f8f6f4 v[106:109], v[18:25], v[50:57], v[106:109]
	v_mfma_f32_16x16x128_f8f6f4 v[94:97], v[26:33], v[42:49], v[94:97]
	v_mfma_f32_16x16x128_f8f6f4 v[90:93], v[18:25], v[42:49], v[90:93]
	v_mfma_f32_16x16x128_f8f6f4 v[78:81], v[26:33], v[34:41], v[78:81]
	v_mfma_f32_16x16x128_f8f6f4 v[74:77], v[18:25], v[34:41], v[74:77]
	v_mfma_f32_16x16x128_f8f6f4 v[118:121], v[10:17], v[58:65], v[118:121]
	v_mfma_f32_16x16x128_f8f6f4 v[114:117], v[2:9], v[58:65], v[114:117]
	v_mfma_f32_16x16x128_f8f6f4 v[102:105], v[10:17], v[50:57], v[102:105]
	v_mfma_f32_16x16x128_f8f6f4 v[98:101], v[2:9], v[50:57], v[98:101]
	v_mfma_f32_16x16x128_f8f6f4 v[86:89], v[10:17], v[42:49], v[86:89]
	v_mfma_f32_16x16x128_f8f6f4 v[82:85], v[2:9], v[42:49], v[82:85]
	v_mfma_f32_16x16x128_f8f6f4 v[70:73], v[10:17], v[34:41], v[70:73]
	v_mfma_f32_16x16x128_f8f6f4 v[66:69], v[2:9], v[34:41], v[66:69]
	s_setprio 0
	s_barrier
	ds_read_b128 v[2:5], v253
	ds_read_b128 v[6:9], v253 offset:1024
	ds_read_b128 v[10:13], v253 offset:2048
	ds_read_b128 v[14:17], v253 offset:3072
	ds_read_b128 v[18:21], v254
	ds_read_b128 v[22:25], v254 offset:1024
	ds_read_b128 v[26:29], v254 offset:2048
	ds_read_b128 v[30:33], v254 offset:3072
	s_add_u32 s100, s28, 0x530000
	s_addc_u32 s101, s29, 0
	s_mov_b32 m0, s42
	ds_read_b128 v[34:37], v226 offset:32768
	ds_read_b128 v[38:41], v226 offset:33792
	ds_read_b128 v[42:45], v226 offset:34816
	ds_read_b128 v[46:49], v226 offset:35840
	ds_read_b128 v[50:53], v226 offset:36864
	ds_read_b128 v[54:57], v226 offset:37888
	ds_read_b128 v[58:61], v226 offset:38912
	ds_read_b128 v[62:65], v226 offset:39936
	global_load_lds_dwordx4 v194, s[100:101]
	s_mov_b32 m0, s43
	s_nop 0
	global_load_lds_dwordx4 v198, s[100:101]
	s_waitcnt lgkmcnt(0)
	s_barrier
	s_setprio 1
	v_mfma_f32_16x16x128_f8f6f4 v[190:193], v[2:9], v[34:41], v[190:193]
	v_mfma_f32_16x16x128_f8f6f4 v[186:189], v[10:17], v[34:41], v[186:189]
	v_mfma_f32_16x16x128_f8f6f4 v[174:177], v[2:9], v[42:49], v[174:177]
	v_mfma_f32_16x16x128_f8f6f4 v[170:173], v[10:17], v[42:49], v[170:173]
	v_mfma_f32_16x16x128_f8f6f4 v[158:161], v[2:9], v[50:57], v[158:161]
	v_mfma_f32_16x16x128_f8f6f4 v[154:157], v[10:17], v[50:57], v[154:157]
	v_mfma_f32_16x16x128_f8f6f4 v[142:145], v[2:9], v[58:65], v[142:145]
	v_mfma_f32_16x16x128_f8f6f4 v[138:141], v[10:17], v[58:65], v[138:141]
	v_mfma_f32_16x16x128_f8f6f4 v[182:185], v[18:25], v[34:41], v[182:185]
	v_mfma_f32_16x16x128_f8f6f4 v[178:181], v[26:33], v[34:41], v[178:181]
	v_mfma_f32_16x16x128_f8f6f4 v[166:169], v[18:25], v[42:49], v[166:169]
	v_mfma_f32_16x16x128_f8f6f4 v[162:165], v[26:33], v[42:49], v[162:165]
	v_mfma_f32_16x16x128_f8f6f4 v[150:153], v[18:25], v[50:57], v[150:153]
	v_mfma_f32_16x16x128_f8f6f4 v[146:149], v[26:33], v[50:57], v[146:149]
	v_mfma_f32_16x16x128_f8f6f4 v[134:137], v[18:25], v[58:65], v[134:137]
	v_mfma_f32_16x16x128_f8f6f4 v[130:133], v[26:33], v[58:65], v[130:133]
	s_setprio 0
	s_waitcnt vmcnt(8)
	s_barrier
	s_mov_b32 m0, s49
	ds_read_b128 v[34:37], v226 offset:49152
	ds_read_b128 v[38:41], v226 offset:50176
	ds_read_b128 v[42:45], v226 offset:51200
	ds_read_b128 v[46:49], v226 offset:52224
	ds_read_b128 v[50:53], v226 offset:53248
	ds_read_b128 v[54:57], v226 offset:54272
	ds_read_b128 v[58:61], v226 offset:55296
	ds_read_b128 v[62:65], v226 offset:56320
	s_add_u32 s98, s26, 0x80
	s_addc_u32 s99, s27, 0
	global_load_lds_dwordx4 v196, s[98:99]
	s_mov_b32 m0, s50
	s_nop 0
	global_load_lds_dwordx4 v200, s[98:99]
	s_mov_b32 m0, s54
	s_add_u32 s100, s72, 0x80
	s_addc_u32 s101, s73, 0
	global_load_lds_dwordx4 v196, s[100:101]
	s_mov_b32 m0, s55
	s_nop 0
	global_load_lds_dwordx4 v200, s[100:101]
	s_mov_b32 m0, s51
	s_add_u32 s98, s28, 0x100
	s_addc_u32 s99, s29, 0
	global_load_lds_dwordx4 v194, s[98:99]
	s_mov_b32 m0, s52
	s_nop 0
	global_load_lds_dwordx4 v198, s[98:99]
	s_waitcnt lgkmcnt(0)
	s_barrier
	s_setprio 1
	v_mfma_f32_16x16x128_f8f6f4 v[126:129], v[2:9], v[34:41], v[126:129]
	v_mfma_f32_16x16x128_f8f6f4 v[122:125], v[10:17], v[34:41], v[122:125]
	v_mfma_f32_16x16x128_f8f6f4 v[110:113], v[2:9], v[42:49], v[110:113]
	v_mfma_f32_16x16x128_f8f6f4 v[106:109], v[10:17], v[42:49], v[106:109]
	v_mfma_f32_16x16x128_f8f6f4 v[94:97], v[2:9], v[50:57], v[94:97]
	v_mfma_f32_16x16x128_f8f6f4 v[90:93], v[10:17], v[50:57], v[90:93]
	v_mfma_f32_16x16x128_f8f6f4 v[78:81], v[2:9], v[58:65], v[78:81]
	v_mfma_f32_16x16x128_f8f6f4 v[74:77], v[10:17], v[58:65], v[74:77]
	v_mfma_f32_16x16x128_f8f6f4 v[118:121], v[18:25], v[34:41], v[118:121]
	v_mfma_f32_16x16x128_f8f6f4 v[114:117], v[26:33], v[34:41], v[114:117]
	v_mfma_f32_16x16x128_f8f6f4 v[102:105], v[18:25], v[42:49], v[102:105]
	v_mfma_f32_16x16x128_f8f6f4 v[98:101], v[26:33], v[42:49], v[98:101]
	v_mfma_f32_16x16x128_f8f6f4 v[86:89], v[18:25], v[50:57], v[86:89]
	v_mfma_f32_16x16x128_f8f6f4 v[82:85], v[26:33], v[50:57], v[82:85]
	v_mfma_f32_16x16x128_f8f6f4 v[70:73], v[18:25], v[58:65], v[70:73]
	v_mfma_f32_16x16x128_f8f6f4 v[66:69], v[26:33], v[58:65], v[66:69]
	s_setprio 0
	s_waitcnt vmcnt(8)
	s_barrier
	s_add_i32 s70, s70, 2
	s_add_u32 s6, s6, 0x200
	s_addc_u32 s7, s7, 0
	s_add_u32 s68, s68, 0x100
	s_addc_u32 s69, s69, 0
	s_cmp_gt_u32 s70, 13
	s_cbranch_scc1 .LBB0_893

.LBB0_889:
	s_add_u32 s26, s4, s6
	s_addc_u32 s27, s5, s7
	s_add_u32 s26, s26, 0x200
	s_addc_u32 s27, s27, 0
	s_waitcnt lgkmcnt(0)
	s_cmpk_eq_i32 s6, 0xe00
	s_cselect_b32 s29, s23, s27
	s_cselect_b32 s28, s22, s26
	s_cselect_b32 s27, s66, s69
	s_cselect_b32 s26, s67, s68
	s_barrier
	s_setprio 1
	s_waitcnt lgkmcnt(0)
	v_mfma_f32_16x16x128_f8f6f4 v[190:193], v[26:33], v[58:65], v[190:193]
	v_mfma_f32_16x16x128_f8f6f4 v[186:189], v[18:25], v[58:65], v[186:189]
	v_mfma_f32_16x16x128_f8f6f4 v[174:177], v[26:33], v[50:57], v[174:177]
	v_mfma_f32_16x16x128_f8f6f4 v[170:173], v[18:25], v[50:57], v[170:173]
	v_mfma_f32_16x16x128_f8f6f4 v[158:161], v[26:33], v[42:49], v[158:161]
	v_mfma_f32_16x16x128_f8f6f4 v[154:157], v[18:25], v[42:49], v[154:157]
	v_mfma_f32_16x16x128_f8f6f4 v[142:145], v[26:33], v[34:41], v[142:145]
	v_mfma_f32_16x16x128_f8f6f4 v[138:141], v[18:25], v[34:41], v[138:141]
	v_mfma_f32_16x16x128_f8f6f4 v[182:185], v[10:17], v[58:65], v[182:185]
	v_mfma_f32_16x16x128_f8f6f4 v[178:181], v[2:9], v[58:65], v[178:181]
	v_mfma_f32_16x16x128_f8f6f4 v[166:169], v[10:17], v[50:57], v[166:169]
	v_mfma_f32_16x16x128_f8f6f4 v[162:165], v[2:9], v[50:57], v[162:165]
	v_mfma_f32_16x16x128_f8f6f4 v[150:153], v[10:17], v[42:49], v[150:153]
	v_mfma_f32_16x16x128_f8f6f4 v[146:149], v[2:9], v[42:49], v[146:149]
	v_mfma_f32_16x16x128_f8f6f4 v[134:137], v[10:17], v[34:41], v[134:137]
	v_mfma_f32_16x16x128_f8f6f4 v[130:133], v[2:9], v[34:41], v[130:133]
	s_setprio 0
	s_barrier
	s_mov_b32 m0, s36
	s_add_u32 s72, s26, 0x40000
	ds_read_b128 v[58:61], v226 offset:16384
	ds_read_b128 v[62:65], v226 offset:17408
	ds_read_b128 v[50:53], v226 offset:18432
	ds_read_b128 v[54:57], v226 offset:19456
	ds_read_b128 v[42:45], v226 offset:20480
	ds_read_b128 v[46:49], v226 offset:21504
	ds_read_b128 v[34:37], v226 offset:22528
	ds_read_b128 v[38:41], v226 offset:23552
	global_load_lds_dwordx4 v196, s[26:27]
	s_mov_b32 m0, s37
	s_addc_u32 s73, s27, 0
	global_load_lds_dwordx4 v200, s[26:27]
	s_mov_b32 m0, s38
	s_nop 0
	global_load_lds_dwordx4 v196, s[72:73]
	s_mov_b32 m0, s39
	s_andn2_b64 vcc, exec, s[30:31]
	global_load_lds_dwordx4 v200, s[72:73]
	s_mov_b32 m0, s40
	s_nop 0
	global_load_lds_dwordx4 v194, s[28:29]
	s_mov_b32 m0, s41
	s_nop 0
	global_load_lds_dwordx4 v198, s[28:29]
	s_cbranch_vccnz .LBB0_892
	s_waitcnt vmcnt(24)
	s_cbranch_execnz .LBB0_885
	s_branch .LBB0_884

.LBB0_1052:
	s_add_u32 s4, s4, 0x17600000
	s_addc_u32 s5, s5, 0
	s_lshl_b32 s6, s6, 5
	s_add_i32 s58, s3, 0x18000
	s_and_b32 s17, s6, 0x60
	s_add_i32 s59, s58, s10
	s_mov_b64 s[6:7], 0x80
	s_lshl_b32 s16, s9, 13
	s_lshl_b32 s18, s17, 7
	v_lshl_add_u64 v[8:9], v[8:9], 0, s[6:7]
	s_mov_b32 m0, s59
	s_add_i32 s60, s59, 0x2000
	s_add_i32 s61, s54, 0x8000
	s_add_i32 s62, s54, 0xa000
	s_waitcnt vmcnt(2)
	s_barrier
	global_load_lds_dwordx4 v[8:9], off
	v_lshl_add_u64 v[6:7], v[6:7], 0, s[6:7]
	s_mov_b32 m0, s60
	s_add_u32 s14, s36, 0x40080
	global_load_lds_dwordx4 v[6:7], off
	v_lshl_add_u64 v[2:3], v[2:3], 0, s[6:7]
	s_mov_b32 m0, s61
	s_addc_u32 s15, s37, 0
	s_add_i32 s63, s3, 0x1c000
	global_load_lds_dwordx4 v[2:3], off
	v_lshl_add_u64 v[2:3], v[4:5], 0, s[6:7]
	s_mov_b32 m0, s62
	s_add_i32 s64, s63, s10
	global_load_lds_dwordx4 v[2:3], off
	v_lshl_add_u64 v[2:3], s[14:15], 0, v[198:199]
	s_mov_b32 m0, s64
	s_add_i32 s65, s64, 0x2000
	global_load_lds_dwordx4 v[2:3], off
	v_lshl_add_u64 v[2:3], s[14:15], 0, v[194:195]
	s_mov_b32 m0, s65
	s_mov_b64 s[14:15], 0x40080
	global_load_lds_dwordx4 v[2:3], off
	v_lshrrev_b32_e32 v3, 1, v10
	v_and_b32_e32 v3, 24, v3
	v_and_b32_e32 v2, 15, v10
	v_lshlrev_b32_e32 v4, 1, v3
	v_lshl_or_b32 v1, s9, 6, v2
	v_lshl_or_b32 v2, v2, 6, v4
	v_lshlrev_b32_e32 v4, 2, v10
	v_and_b32_e32 v4, 32, v4
	v_bitop3_b32 v5, v2, s16, v4 bitop3:0xde
	v_bitop3_b32 v222, v2, s18, v4 bitop3:0xde
	v_add_u32_e32 v253, s58, v222
	v_add_u32_e32 v254, s63, v222
	v_lshlrev_b32_e32 v2, 14, v11
	v_and_b32_e32 v2, 0xffff8000, v2
	v_or_b32_e32 v223, s17, v3
	v_lshl_add_u32 v2, v12, 11, v2
	v_and_b32_e32 v3, 1, v11
	v_lshl_or_b32 v2, v3, 6, v2
	v_lshl_add_u32 v2, v13, 1, v2
	v_mov_b32_e32 v3, v199
	v_lshl_add_u64 v[202:203], v[2:3], 0, s[14:15]
	v_lshlrev_b32_e32 v2, 14, v15
	v_and_b32_e32 v2, 0xffff8000, v2
	v_lshl_add_u32 v2, v14, 11, v2
	v_and_b32_e32 v3, 1, v15
	s_waitcnt vmcnt(6)
	v_lshl_or_b32 v2, v3, 6, v2
	s_cmpk_lt_u32 s8, 0x100
	v_lshl_add_u32 v2, v16, 1, v2
	v_mov_b32_e32 v3, v199
	s_sext_i32_i8 s72, s2
	s_cselect_b64 s[8:9], -1, 0
	s_ashr_i32 s66, s33, 31
	v_lshl_add_u64 v[204:205], v[2:3], 0, s[14:15]
	s_mov_b32 s34, 0
	v_mov_b64_e32 v[206:207], 0x240
	v_mov_b64_e32 v[208:209], 0x23f
	v_add_u32_e32 v224, s12, v222
	v_add_u32_e32 v225, s13, v222
	v_add_u32_e32 v226, s3, v5
	v_mov_b32_e32 v227, 0x7f7f7f7f
	s_mov_b32 s10, 0x3a000000
	s_mov_b64 s[12:13], 0x80000
	s_mov_b32 s67, 0x80000
	s_mov_b64 s[14:15], 0x90000
	s_mov_b32 s68, 0x90000
	s_mov_b64 s[16:17], 0xa0000
	s_mov_b32 s69, 0xa0000
	s_mov_b64 s[18:19], 0xb0000
	s_mov_b32 s70, 0xb0000
	s_barrier
	s_branch .LBB0_1055

.LBB0_1062:
	s_waitcnt lgkmcnt(0)
	s_barrier
	s_setprio 1
	v_mfma_f32_16x16x128_f8f6f4 v[126:129], v[26:33], v[58:65], v[126:129]
	v_mfma_f32_16x16x128_f8f6f4 v[122:125], v[18:25], v[58:65], v[122:125]
	v_mfma_f32_16x16x128_f8f6f4 v[114:117], v[26:33], v[50:57], v[114:117]
	v_mfma_f32_16x16x128_f8f6f4 v[106:109], v[18:25], v[50:57], v[106:109]
	v_mfma_f32_16x16x128_f8f6f4 v[98:101], v[26:33], v[42:49], v[98:101]
	v_mfma_f32_16x16x128_f8f6f4 v[90:93], v[18:25], v[42:49], v[90:93]
	v_mfma_f32_16x16x128_f8f6f4 v[82:85], v[26:33], v[34:41], v[82:85]
	v_mfma_f32_16x16x128_f8f6f4 v[74:77], v[18:25], v[34:41], v[74:77]
	v_mfma_f32_16x16x128_f8f6f4 v[118:121], v[10:17], v[58:65], v[118:121]
	v_mfma_f32_16x16x128_f8f6f4 v[110:113], v[2:9], v[58:65], v[110:113]
	v_mfma_f32_16x16x128_f8f6f4 v[102:105], v[10:17], v[50:57], v[102:105]
	v_mfma_f32_16x16x128_f8f6f4 v[94:97], v[2:9], v[50:57], v[94:97]
	v_mfma_f32_16x16x128_f8f6f4 v[86:89], v[10:17], v[42:49], v[86:89]
	v_mfma_f32_16x16x128_f8f6f4 v[78:81], v[2:9], v[42:49], v[78:81]
	v_mfma_f32_16x16x128_f8f6f4 v[70:73], v[10:17], v[34:41], v[70:73]
	v_mfma_f32_16x16x128_f8f6f4 v[66:69], v[2:9], v[34:41], v[66:69]
	s_setprio 0
	s_barrier
	ds_read_b128 v[2:5], v253
	ds_read_b128 v[6:9], v253 offset:1024
	ds_read_b128 v[10:13], v253 offset:2048
	ds_read_b128 v[14:17], v253 offset:3072
	ds_read_b128 v[18:21], v254
	ds_read_b128 v[22:25], v254 offset:1024
	ds_read_b128 v[26:29], v254 offset:2048
	ds_read_b128 v[30:33], v254 offset:3072
	s_add_u32 s100, s40, 0x40000
	s_addc_u32 s101, s41, 0
	s_mov_b32 m0, s56
	ds_read_b128 v[34:37], v226 offset:32768
	ds_read_b128 v[38:41], v226 offset:33792
	ds_read_b128 v[42:45], v226 offset:34816
	ds_read_b128 v[46:49], v226 offset:35840
	ds_read_b128 v[50:53], v226 offset:36864
	ds_read_b128 v[54:57], v226 offset:37888
	ds_read_b128 v[58:61], v226 offset:38912
	ds_read_b128 v[62:65], v226 offset:39936
	global_load_lds_dwordx4 v200, s[100:101]
	s_mov_b32 m0, s57
	s_nop 0
	global_load_lds_dwordx4 v196, s[100:101]
	s_waitcnt lgkmcnt(0)
	s_barrier
	s_setprio 1
	v_mfma_f32_16x16x128_f8f6f4 v[190:193], v[2:9], v[34:41], v[190:193]
	v_mfma_f32_16x16x128_f8f6f4 v[186:189], v[10:17], v[34:41], v[186:189]
	v_mfma_f32_16x16x128_f8f6f4 v[178:181], v[2:9], v[42:49], v[178:181]
	v_mfma_f32_16x16x128_f8f6f4 v[170:173], v[10:17], v[42:49], v[170:173]
	v_mfma_f32_16x16x128_f8f6f4 v[162:165], v[2:9], v[50:57], v[162:165]
	v_mfma_f32_16x16x128_f8f6f4 v[154:157], v[10:17], v[50:57], v[154:157]
	v_mfma_f32_16x16x128_f8f6f4 v[146:149], v[2:9], v[58:65], v[146:149]
	v_mfma_f32_16x16x128_f8f6f4 v[138:141], v[10:17], v[58:65], v[138:141]
	v_mfma_f32_16x16x128_f8f6f4 v[182:185], v[18:25], v[34:41], v[182:185]
	v_mfma_f32_16x16x128_f8f6f4 v[174:177], v[26:33], v[34:41], v[174:177]
	v_mfma_f32_16x16x128_f8f6f4 v[166:169], v[18:25], v[42:49], v[166:169]
	v_mfma_f32_16x16x128_f8f6f4 v[158:161], v[26:33], v[42:49], v[158:161]
	v_mfma_f32_16x16x128_f8f6f4 v[150:153], v[18:25], v[50:57], v[150:153]
	v_mfma_f32_16x16x128_f8f6f4 v[142:145], v[26:33], v[50:57], v[142:145]
	v_mfma_f32_16x16x128_f8f6f4 v[134:137], v[18:25], v[58:65], v[134:137]
	v_mfma_f32_16x16x128_f8f6f4 v[130:133], v[26:33], v[58:65], v[130:133]
	s_setprio 0
	s_waitcnt vmcnt(8)
	s_barrier
	s_mov_b32 m0, s59
	ds_read_b128 v[34:37], v226 offset:49152
	ds_read_b128 v[38:41], v226 offset:50176
	ds_read_b128 v[42:45], v226 offset:51200
	ds_read_b128 v[46:49], v226 offset:52224
	ds_read_b128 v[50:53], v226 offset:53248
	ds_read_b128 v[54:57], v226 offset:54272
	ds_read_b128 v[58:61], v226 offset:55296
	ds_read_b128 v[62:65], v226 offset:56320
	s_add_u32 s98, s38, 0x80
	s_addc_u32 s99, s39, 0
	global_load_lds_dwordx4 v198, s[98:99]
	s_mov_b32 m0, s60
	s_nop 0
	global_load_lds_dwordx4 v194, s[98:99]
	s_mov_b32 m0, s64
	s_add_u32 s100, s78, 0x80
	s_addc_u32 s101, s79, 0
	global_load_lds_dwordx4 v198, s[100:101]
	s_mov_b32 m0, s65
	s_nop 0
	global_load_lds_dwordx4 v194, s[100:101]
	s_mov_b32 m0, s61
	s_add_u32 s98, s40, 0x80
	s_addc_u32 s99, s41, 0
	global_load_lds_dwordx4 v200, s[98:99]
	s_mov_b32 m0, s62
	s_nop 0
	global_load_lds_dwordx4 v196, s[98:99]
	s_waitcnt lgkmcnt(0)
	s_barrier
	s_setprio 1
	v_mfma_f32_16x16x128_f8f6f4 v[126:129], v[2:9], v[34:41], v[126:129]
	v_mfma_f32_16x16x128_f8f6f4 v[122:125], v[10:17], v[34:41], v[122:125]
	v_mfma_f32_16x16x128_f8f6f4 v[114:117], v[2:9], v[42:49], v[114:117]
	v_mfma_f32_16x16x128_f8f6f4 v[106:109], v[10:17], v[42:49], v[106:109]
	v_mfma_f32_16x16x128_f8f6f4 v[98:101], v[2:9], v[50:57], v[98:101]
	v_mfma_f32_16x16x128_f8f6f4 v[90:93], v[10:17], v[50:57], v[90:93]
	v_mfma_f32_16x16x128_f8f6f4 v[82:85], v[2:9], v[58:65], v[82:85]
	v_mfma_f32_16x16x128_f8f6f4 v[74:77], v[10:17], v[58:65], v[74:77]
	v_mfma_f32_16x16x128_f8f6f4 v[118:121], v[18:25], v[34:41], v[118:121]
	v_mfma_f32_16x16x128_f8f6f4 v[110:113], v[26:33], v[34:41], v[110:113]
	v_mfma_f32_16x16x128_f8f6f4 v[102:105], v[18:25], v[42:49], v[102:105]
	v_mfma_f32_16x16x128_f8f6f4 v[94:97], v[26:33], v[42:49], v[94:97]
	v_mfma_f32_16x16x128_f8f6f4 v[86:89], v[18:25], v[50:57], v[86:89]
	v_mfma_f32_16x16x128_f8f6f4 v[78:81], v[26:33], v[50:57], v[78:81]
	v_mfma_f32_16x16x128_f8f6f4 v[70:73], v[18:25], v[58:65], v[70:73]
	v_mfma_f32_16x16x128_f8f6f4 v[66:69], v[26:33], v[58:65], v[66:69]
	s_setprio 0
	s_waitcnt vmcnt(8)
	s_barrier
	s_add_i32 s77, s77, 2
	s_add_u32 s36, s36, 0x100
	s_addc_u32 s37, s37, 0
	s_cmp_gt_u32 s77, 13
	s_cbranch_scc1 .LBB0_1070

.LBB0_1066:
	s_add_u32 s38, s30, s36
	s_addc_u32 s39, s31, s37
	s_add_u32 s38, s38, 0x100
	s_addc_u32 s39, s39, 0
	s_add_u32 s78, s75, s36
	s_addc_u32 s79, s76, s37
	s_waitcnt lgkmcnt(0)
	s_cmpk_eq_i32 s36, 0x700
	s_cselect_b32 s41, s21, s39
	s_cselect_b32 s40, s73, s38
	s_cselect_b32 s39, s23, s79
	s_cselect_b32 s38, s74, s78
	s_barrier
	s_setprio 1
	s_waitcnt lgkmcnt(0)
	v_mfma_f32_16x16x128_f8f6f4 v[190:193], v[26:33], v[58:65], v[190:193]
	v_mfma_f32_16x16x128_f8f6f4 v[186:189], v[18:25], v[58:65], v[186:189]
	v_mfma_f32_16x16x128_f8f6f4 v[178:181], v[26:33], v[50:57], v[178:181]
	v_mfma_f32_16x16x128_f8f6f4 v[170:173], v[18:25], v[50:57], v[170:173]
	v_mfma_f32_16x16x128_f8f6f4 v[162:165], v[26:33], v[42:49], v[162:165]
	v_mfma_f32_16x16x128_f8f6f4 v[154:157], v[18:25], v[42:49], v[154:157]
	v_mfma_f32_16x16x128_f8f6f4 v[146:149], v[26:33], v[34:41], v[146:149]
	v_mfma_f32_16x16x128_f8f6f4 v[138:141], v[18:25], v[34:41], v[138:141]
	v_mfma_f32_16x16x128_f8f6f4 v[182:185], v[10:17], v[58:65], v[182:185]
	v_mfma_f32_16x16x128_f8f6f4 v[174:177], v[2:9], v[58:65], v[174:177]
	v_mfma_f32_16x16x128_f8f6f4 v[166:169], v[10:17], v[50:57], v[166:169]
	v_mfma_f32_16x16x128_f8f6f4 v[158:161], v[2:9], v[50:57], v[158:161]
	v_mfma_f32_16x16x128_f8f6f4 v[150:153], v[10:17], v[42:49], v[150:153]
	v_mfma_f32_16x16x128_f8f6f4 v[142:145], v[2:9], v[42:49], v[142:145]
	v_mfma_f32_16x16x128_f8f6f4 v[134:137], v[10:17], v[34:41], v[134:137]
	v_mfma_f32_16x16x128_f8f6f4 v[130:133], v[2:9], v[34:41], v[130:133]
	s_setprio 0
	s_barrier
	s_mov_b32 m0, s29
	s_add_u32 s78, s38, 0x40000
	ds_read_b128 v[58:61], v226 offset:16384
	ds_read_b128 v[62:65], v226 offset:17408
	ds_read_b128 v[50:53], v226 offset:18432
	ds_read_b128 v[54:57], v226 offset:19456
	ds_read_b128 v[42:45], v226 offset:20480
	ds_read_b128 v[46:49], v226 offset:21504
	ds_read_b128 v[34:37], v226 offset:22528
	ds_read_b128 v[38:41], v226 offset:23552
	global_load_lds_dwordx4 v198, s[38:39]
	s_mov_b32 m0, s51
	s_addc_u32 s79, s39, 0
	global_load_lds_dwordx4 v194, s[38:39]
	s_mov_b32 m0, s52
	s_nop 0
	global_load_lds_dwordx4 v198, s[78:79]
	s_mov_b32 m0, s53
	s_andn2_b64 vcc, exec, s[42:43]
	global_load_lds_dwordx4 v194, s[78:79]
	s_mov_b32 m0, s54
	s_nop 0
	global_load_lds_dwordx4 v200, s[40:41]
	s_mov_b32 m0, s55
	s_nop 0
	global_load_lds_dwordx4 v196, s[40:41]
	s_cbranch_vccnz .LBB0_1069
	s_waitcnt vmcnt(24)
	s_cbranch_execnz .LBB0_1062
	s_branch .LBB0_1061

.LBB0_1215:
	s_add_u32 s20, s5, 0x30200000
	s_addc_u32 s21, s6, 0
	s_add_u32 s22, s5, 0x17600000
	s_addc_u32 s23, s6, 0
	s_add_u32 s72, s5, 0x18600000
	s_addc_u32 s73, s6, 0
	s_lshl_b32 s3, s3, 5
	s_add_i32 s74, s14, 0x18000
	s_and_b32 s35, s3, 0x60
	s_add_i32 s75, s74, s2
	s_mov_b64 s[24:25], 0x80
	s_lshl_b32 s5, s63, 6
	s_lshl_b32 s8, s63, 13
	s_lshl_b32 s3, s35, 7
	v_lshl_add_u64 v[8:9], v[8:9], 0, s[24:25]
	s_mov_b32 m0, s75
	s_add_i32 s76, s75, 0x2000
	s_add_i32 s77, s68, 0x8000
	s_add_i32 s78, s68, 0xa000
	s_waitcnt vmcnt(2)
	s_barrier
	global_load_lds_dwordx4 v[8:9], off
	v_lshl_add_u64 v[6:7], v[6:7], 0, s[24:25]
	s_mov_b32 m0, s76
	s_add_u32 s6, s50, 0x80080
	global_load_lds_dwordx4 v[6:7], off
	v_lshl_add_u64 v[2:3], v[2:3], 0, s[24:25]
	s_mov_b32 m0, s77
	s_addc_u32 s7, s51, 0
	s_add_i32 s79, s14, 0x1c000
	global_load_lds_dwordx4 v[2:3], off
	v_lshl_add_u64 v[2:3], v[4:5], 0, s[24:25]
	s_mov_b32 m0, s78
	s_add_i32 s80, s79, s2
	global_load_lds_dwordx4 v[2:3], off
	v_lshl_add_u64 v[2:3], s[6:7], 0, v[196:197]
	s_mov_b32 m0, s80
	s_add_i32 s81, s80, 0x2000
	global_load_lds_dwordx4 v[2:3], off
	v_lshl_add_u64 v[2:3], s[6:7], 0, v[200:201]
	s_mov_b32 m0, s81
	v_and_b32_e32 v202, 15, v1
	global_load_lds_dwordx4 v[2:3], off
	v_lshrrev_b32_e32 v2, 1, v1
	v_and_b32_e32 v2, 24, v2
	v_lshlrev_b32_e32 v3, 1, v2
	v_lshlrev_b32_e32 v1, 2, v1
	v_or_b32_e32 v203, s35, v2
	v_lshlrev_b32_e32 v2, 15, v13
	v_lshl_or_b32 v3, v202, 6, v3
	v_and_b32_e32 v1, 32, v1
	v_and_b32_e32 v2, 0xffff0000, v2
	v_bitop3_b32 v4, v3, s8, v1 bitop3:0xde
	v_bitop3_b32 v1, v3, s3, v1 bitop3:0xde
	v_add_u32_e32 v253, s74, v1
	v_add_u32_e32 v254, s79, v1
	v_lshl_add_u32 v2, v14, 12, v2
	v_and_b32_e32 v3, 1, v13
	v_lshl_or_b32 v2, v3, 6, v2
	s_mov_b64 s[36:37], 0x80080
	v_lshl_add_u32 v2, v15, 1, v2
	v_mov_b32_e32 v3, v197
	s_cmpk_lt_u32 s4, 0x100
	v_lshl_add_u64 v[208:209], v[2:3], 0, s[36:37]
	v_lshlrev_b32_e32 v2, 15, v10
	s_cselect_b64 s[26:27], -1, 0
	s_ashr_i32 s2, s5, 31
	s_ashr_i32 s82, s33, 31
	s_ashr_i32 s83, s58, 31
	v_and_b32_e32 v2, 0xffff0000, v2
	s_add_u32 s28, s0, 0x5800
	v_lshl_add_u32 v2, v11, 12, v2
	v_and_b32_e32 v3, 1, v10
	s_waitcnt vmcnt(6)
	s_addc_u32 s29, s1, 0
	v_lshl_or_b32 v2, v3, 6, v2
	s_add_u32 s30, s0, 0xb000
	v_lshl_add_u32 v2, v12, 1, v2
	v_mov_b32_e32 v3, v197
	v_or_b32_e32 v204, s5, v202
	v_mov_b32_e32 v205, s2
	v_cmp_eq_u32_e64 s[2:3], 15, v202
	s_mov_b32 s48, 0
	v_cmp_eq_u32_e64 s[4:5], 0, v202
	v_cmp_ne_u32_e64 s[6:7], 15, v202
	v_cmp_ne_u32_e64 s[8:9], 0, v202
	v_cmp_gt_u32_e64 s[10:11], 2, v202
	v_cmp_lt_u32_e64 s[12:13], 13, v202
	v_add_u32_e32 v206, -12, v202
	v_mov_b32_e32 v207, v197
	s_addc_u32 s31, s1, 0
	v_lshl_add_u64 v[210:211], v[2:3], 0, s[36:37]
	v_mov_b64_e32 v[212:213], 0xc60
	v_mov_b64_e32 v[214:215], 0xc5f
	s_movk_i32 s84, 0x18d
	v_add_u32_e32 v228, s15, v1
	v_add_u32_e32 v229, s34, v1
	v_add_u32_e32 v231, s14, v4
	s_movk_i32 s85, 0x2c00
	s_mov_b32 s86, 0x2c000
	s_mov_b32 s87, 0x58000
	s_mov_b32 s88, 0x18c000
	s_mov_b32 s89, 0x1b8000
	v_mov_b32_e32 v232, 0x2c00
	s_barrier
	s_branch .LBB0_1218

.LBB0_1225:
	s_waitcnt lgkmcnt(0)
	s_barrier
	s_setprio 1
	v_mfma_f32_16x16x32_bf16 v[54:57], v[82:85], v[186:189], v[54:57]
	v_mfma_f32_16x16x32_bf16 v[46:49], v[90:93], v[186:189], v[46:49]
	v_mfma_f32_16x16x32_bf16 v[50:53], v[82:85], v[178:181], v[50:53]
	v_mfma_f32_16x16x32_bf16 v[38:41], v[90:93], v[178:181], v[38:41]
	v_mfma_f32_16x16x32_bf16 v[30:33], v[82:85], v[170:173], v[30:33]
	v_mfma_f32_16x16x32_bf16 v[22:25], v[90:93], v[170:173], v[22:25]
	v_mfma_f32_16x16x32_bf16 v[14:17], v[82:85], v[162:165], v[14:17]
	v_mfma_f32_16x16x32_bf16 v[10:13], v[90:93], v[162:165], v[10:13]
	v_mfma_f32_16x16x32_bf16 v[54:57], v[86:89], v[190:193], v[54:57]
	v_mfma_f32_16x16x32_bf16 v[46:49], v[94:97], v[190:193], v[46:49]
	v_mfma_f32_16x16x32_bf16 v[50:53], v[86:89], v[182:185], v[50:53]
	v_mfma_f32_16x16x32_bf16 v[38:41], v[94:97], v[182:185], v[38:41]
	v_mfma_f32_16x16x32_bf16 v[30:33], v[86:89], v[174:177], v[30:33]
	v_mfma_f32_16x16x32_bf16 v[22:25], v[94:97], v[174:177], v[22:25]
	v_mfma_f32_16x16x32_bf16 v[14:17], v[86:89], v[166:169], v[14:17]
	v_mfma_f32_16x16x32_bf16 v[10:13], v[94:97], v[166:169], v[10:13]
	v_mfma_f32_16x16x32_bf16 v[62:65], v[66:69], v[186:189], v[62:65]
	v_mfma_f32_16x16x32_bf16 v[58:61], v[74:77], v[186:189], v[58:61]
	v_mfma_f32_16x16x32_bf16 v[42:45], v[66:69], v[178:181], v[42:45]
	v_mfma_f32_16x16x32_bf16 v[34:37], v[74:77], v[178:181], v[34:37]
	v_mfma_f32_16x16x32_bf16 v[26:29], v[66:69], v[170:173], v[26:29]
	v_mfma_f32_16x16x32_bf16 v[18:21], v[74:77], v[170:173], v[18:21]
	v_mfma_f32_16x16x32_bf16 v[6:9], v[66:69], v[162:165], v[6:9]
	v_mfma_f32_16x16x32_bf16 v[2:5], v[74:77], v[162:165], v[2:5]
	v_mfma_f32_16x16x32_bf16 v[62:65], v[70:73], v[190:193], v[62:65]
	v_mfma_f32_16x16x32_bf16 v[58:61], v[78:81], v[190:193], v[58:61]
	v_mfma_f32_16x16x32_bf16 v[42:45], v[70:73], v[182:185], v[42:45]
	v_mfma_f32_16x16x32_bf16 v[34:37], v[78:81], v[182:185], v[34:37]
	v_mfma_f32_16x16x32_bf16 v[26:29], v[70:73], v[174:177], v[26:29]
	v_mfma_f32_16x16x32_bf16 v[18:21], v[78:81], v[174:177], v[18:21]
	v_mfma_f32_16x16x32_bf16 v[6:9], v[70:73], v[166:169], v[6:9]
	v_mfma_f32_16x16x32_bf16 v[2:5], v[78:81], v[166:169], v[2:5]
	s_setprio 0
	s_barrier
	ds_read_b128 v[66:69], v253
	ds_read_b128 v[70:73], v253 offset:1024
	ds_read_b128 v[74:77], v253 offset:2048
	ds_read_b128 v[78:81], v253 offset:3072
	ds_read_b128 v[82:85], v254
	ds_read_b128 v[86:89], v254 offset:1024
	ds_read_b128 v[90:93], v254 offset:2048
	ds_read_b128 v[94:97], v254 offset:3072
	s_add_u32 s100, s54, 0x80000
	s_addc_u32 s101, s55, 0
	s_mov_b32 m0, s70
	ds_read_b128 v[162:165], v231 offset:32768
	ds_read_b128 v[166:169], v231 offset:33792
	ds_read_b128 v[170:173], v231 offset:34816
	ds_read_b128 v[174:177], v231 offset:35840
	ds_read_b128 v[178:181], v231 offset:36864
	ds_read_b128 v[182:185], v231 offset:37888
	ds_read_b128 v[186:189], v231 offset:38912
	ds_read_b128 v[190:193], v231 offset:39936
	global_load_lds_dwordx4 v194, s[100:101]
	s_mov_b32 m0, s71
	s_nop 0
	global_load_lds_dwordx4 v198, s[100:101]
	s_waitcnt lgkmcnt(0)
	s_barrier
	s_setprio 1
	v_mfma_f32_16x16x32_bf16 v[150:153], v[66:69], v[162:165], v[150:153]
	v_mfma_f32_16x16x32_bf16 v[142:145], v[74:77], v[162:165], v[142:145]
	v_mfma_f32_16x16x32_bf16 v[146:149], v[66:69], v[170:173], v[146:149]
	v_mfma_f32_16x16x32_bf16 v[134:137], v[74:77], v[170:173], v[134:137]
	v_mfma_f32_16x16x32_bf16 v[126:129], v[66:69], v[178:181], v[126:129]
	v_mfma_f32_16x16x32_bf16 v[118:121], v[74:77], v[178:181], v[118:121]
	v_mfma_f32_16x16x32_bf16 v[110:113], v[66:69], v[186:189], v[110:113]
	v_mfma_f32_16x16x32_bf16 v[106:109], v[74:77], v[186:189], v[106:109]
	v_mfma_f32_16x16x32_bf16 v[150:153], v[70:73], v[166:169], v[150:153]
	v_mfma_f32_16x16x32_bf16 v[142:145], v[78:81], v[166:169], v[142:145]
	v_mfma_f32_16x16x32_bf16 v[146:149], v[70:73], v[174:177], v[146:149]
	v_mfma_f32_16x16x32_bf16 v[134:137], v[78:81], v[174:177], v[134:137]
	v_mfma_f32_16x16x32_bf16 v[126:129], v[70:73], v[182:185], v[126:129]
	v_mfma_f32_16x16x32_bf16 v[118:121], v[78:81], v[182:185], v[118:121]
	v_mfma_f32_16x16x32_bf16 v[110:113], v[70:73], v[190:193], v[110:113]
	v_mfma_f32_16x16x32_bf16 v[106:109], v[78:81], v[190:193], v[106:109]
	v_mfma_f32_16x16x32_bf16 v[158:161], v[82:85], v[162:165], v[158:161]
	v_mfma_f32_16x16x32_bf16 v[154:157], v[90:93], v[162:165], v[154:157]
	v_mfma_f32_16x16x32_bf16 v[138:141], v[82:85], v[170:173], v[138:141]
	v_mfma_f32_16x16x32_bf16 v[130:133], v[90:93], v[170:173], v[130:133]
	v_mfma_f32_16x16x32_bf16 v[122:125], v[82:85], v[178:181], v[122:125]
	v_mfma_f32_16x16x32_bf16 v[114:117], v[90:93], v[178:181], v[114:117]
	v_mfma_f32_16x16x32_bf16 v[102:105], v[82:85], v[186:189], v[102:105]
	v_mfma_f32_16x16x32_bf16 v[98:101], v[90:93], v[186:189], v[98:101]
	v_mfma_f32_16x16x32_bf16 v[158:161], v[86:89], v[166:169], v[158:161]
	v_mfma_f32_16x16x32_bf16 v[154:157], v[94:97], v[166:169], v[154:157]
	v_mfma_f32_16x16x32_bf16 v[138:141], v[86:89], v[174:177], v[138:141]
	v_mfma_f32_16x16x32_bf16 v[130:133], v[94:97], v[174:177], v[130:133]
	v_mfma_f32_16x16x32_bf16 v[122:125], v[86:89], v[182:185], v[122:125]
	v_mfma_f32_16x16x32_bf16 v[114:117], v[94:97], v[182:185], v[114:117]
	v_mfma_f32_16x16x32_bf16 v[102:105], v[86:89], v[190:193], v[102:105]
	v_mfma_f32_16x16x32_bf16 v[98:101], v[94:97], v[190:193], v[98:101]
	s_setprio 0
	s_waitcnt vmcnt(8)
	s_barrier
	s_mov_b32 m0, s75
	ds_read_b128 v[162:165], v231 offset:49152
	ds_read_b128 v[166:169], v231 offset:50176
	ds_read_b128 v[170:173], v231 offset:51200
	ds_read_b128 v[174:177], v231 offset:52224
	ds_read_b128 v[178:181], v231 offset:53248
	ds_read_b128 v[182:185], v231 offset:54272
	ds_read_b128 v[186:189], v231 offset:55296
	ds_read_b128 v[190:193], v231 offset:56320
	s_add_u32 s98, s52, 0x80
	s_addc_u32 s99, s53, 0
	global_load_lds_dwordx4 v196, s[98:99]
	s_mov_b32 m0, s76
	s_nop 0
	global_load_lds_dwordx4 v200, s[98:99]
	s_mov_b32 m0, s80
	s_add_u32 s100, s94, 0x80
	s_addc_u32 s101, s95, 0
	global_load_lds_dwordx4 v196, s[100:101]
	s_mov_b32 m0, s81
	s_nop 0
	global_load_lds_dwordx4 v200, s[100:101]
	s_mov_b32 m0, s77
	s_add_u32 s98, s54, 0x80
	s_addc_u32 s99, s55, 0
	global_load_lds_dwordx4 v194, s[98:99]
	s_mov_b32 m0, s78
	s_nop 0
	global_load_lds_dwordx4 v198, s[98:99]
	s_waitcnt lgkmcnt(0)
	s_barrier
	s_setprio 1
	v_mfma_f32_16x16x32_bf16 v[54:57], v[66:69], v[162:165], v[54:57]
	v_mfma_f32_16x16x32_bf16 v[46:49], v[74:77], v[162:165], v[46:49]
	v_mfma_f32_16x16x32_bf16 v[50:53], v[66:69], v[170:173], v[50:53]
	v_mfma_f32_16x16x32_bf16 v[38:41], v[74:77], v[170:173], v[38:41]
	v_mfma_f32_16x16x32_bf16 v[30:33], v[66:69], v[178:181], v[30:33]
	v_mfma_f32_16x16x32_bf16 v[22:25], v[74:77], v[178:181], v[22:25]
	v_mfma_f32_16x16x32_bf16 v[14:17], v[66:69], v[186:189], v[14:17]
	v_mfma_f32_16x16x32_bf16 v[10:13], v[74:77], v[186:189], v[10:13]
	v_mfma_f32_16x16x32_bf16 v[54:57], v[70:73], v[166:169], v[54:57]
	v_mfma_f32_16x16x32_bf16 v[46:49], v[78:81], v[166:169], v[46:49]
	v_mfma_f32_16x16x32_bf16 v[50:53], v[70:73], v[174:177], v[50:53]
	v_mfma_f32_16x16x32_bf16 v[38:41], v[78:81], v[174:177], v[38:41]
	v_mfma_f32_16x16x32_bf16 v[30:33], v[70:73], v[182:185], v[30:33]
	v_mfma_f32_16x16x32_bf16 v[22:25], v[78:81], v[182:185], v[22:25]
	v_mfma_f32_16x16x32_bf16 v[14:17], v[70:73], v[190:193], v[14:17]
	v_mfma_f32_16x16x32_bf16 v[10:13], v[78:81], v[190:193], v[10:13]
	v_mfma_f32_16x16x32_bf16 v[62:65], v[82:85], v[162:165], v[62:65]
	v_mfma_f32_16x16x32_bf16 v[58:61], v[90:93], v[162:165], v[58:61]
	v_mfma_f32_16x16x32_bf16 v[42:45], v[82:85], v[170:173], v[42:45]
	v_mfma_f32_16x16x32_bf16 v[34:37], v[90:93], v[170:173], v[34:37]
	v_mfma_f32_16x16x32_bf16 v[26:29], v[82:85], v[178:181], v[26:29]
	v_mfma_f32_16x16x32_bf16 v[18:21], v[90:93], v[178:181], v[18:21]
	v_mfma_f32_16x16x32_bf16 v[6:9], v[82:85], v[186:189], v[6:9]
	v_mfma_f32_16x16x32_bf16 v[2:5], v[90:93], v[186:189], v[2:5]
	v_mfma_f32_16x16x32_bf16 v[62:65], v[86:89], v[166:169], v[62:65]
	v_mfma_f32_16x16x32_bf16 v[58:61], v[94:97], v[166:169], v[58:61]
	v_mfma_f32_16x16x32_bf16 v[42:45], v[86:89], v[174:177], v[42:45]
	v_mfma_f32_16x16x32_bf16 v[34:37], v[94:97], v[174:177], v[34:37]
	v_mfma_f32_16x16x32_bf16 v[26:29], v[86:89], v[182:185], v[26:29]
	v_mfma_f32_16x16x32_bf16 v[18:21], v[94:97], v[182:185], v[18:21]
	v_mfma_f32_16x16x32_bf16 v[6:9], v[86:89], v[190:193], v[6:9]
	v_mfma_f32_16x16x32_bf16 v[2:5], v[94:97], v[190:193], v[2:5]
	s_setprio 0
	s_waitcnt vmcnt(8)
	s_barrier
	s_add_i32 s93, s93, 2
	s_add_u32 s50, s50, 0x100
	s_addc_u32 s51, s51, 0
	s_cmp_gt_u32 s93, 29
	s_cbranch_scc1 .LBB0_1233

.LBB0_1229:
	s_add_u32 s52, s46, s50
	s_addc_u32 s53, s47, s51
	s_add_u32 s52, s52, 0x100
	s_addc_u32 s53, s53, 0
	s_add_u32 s94, s91, s50
	s_addc_u32 s95, s92, s51
	s_waitcnt lgkmcnt(0)
	s_cmpk_eq_i32 s50, 0xf00
	s_cselect_b32 s55, s35, s53
	s_cselect_b32 s54, s43, s52
	s_cselect_b32 s53, s37, s95
	s_cselect_b32 s52, s45, s94
	s_barrier
	s_setprio 1
	s_waitcnt lgkmcnt(0)
	v_mfma_f32_16x16x32_bf16 v[150:153], v[82:85], v[186:189], v[150:153]
	v_mfma_f32_16x16x32_bf16 v[142:145], v[90:93], v[186:189], v[142:145]
	v_mfma_f32_16x16x32_bf16 v[146:149], v[82:85], v[178:181], v[146:149]
	v_mfma_f32_16x16x32_bf16 v[134:137], v[90:93], v[178:181], v[134:137]
	v_mfma_f32_16x16x32_bf16 v[126:129], v[82:85], v[170:173], v[126:129]
	v_mfma_f32_16x16x32_bf16 v[118:121], v[90:93], v[170:173], v[118:121]
	v_mfma_f32_16x16x32_bf16 v[110:113], v[82:85], v[162:165], v[110:113]
	v_mfma_f32_16x16x32_bf16 v[106:109], v[90:93], v[162:165], v[106:109]
	v_mfma_f32_16x16x32_bf16 v[150:153], v[86:89], v[190:193], v[150:153]
	v_mfma_f32_16x16x32_bf16 v[142:145], v[94:97], v[190:193], v[142:145]
	v_mfma_f32_16x16x32_bf16 v[146:149], v[86:89], v[182:185], v[146:149]
	v_mfma_f32_16x16x32_bf16 v[134:137], v[94:97], v[182:185], v[134:137]
	v_mfma_f32_16x16x32_bf16 v[126:129], v[86:89], v[174:177], v[126:129]
	v_mfma_f32_16x16x32_bf16 v[118:121], v[94:97], v[174:177], v[118:121]
	v_mfma_f32_16x16x32_bf16 v[110:113], v[86:89], v[166:169], v[110:113]
	v_mfma_f32_16x16x32_bf16 v[106:109], v[94:97], v[166:169], v[106:109]
	v_mfma_f32_16x16x32_bf16 v[158:161], v[66:69], v[186:189], v[158:161]
	v_mfma_f32_16x16x32_bf16 v[154:157], v[74:77], v[186:189], v[154:157]
	v_mfma_f32_16x16x32_bf16 v[138:141], v[66:69], v[178:181], v[138:141]
	v_mfma_f32_16x16x32_bf16 v[130:133], v[74:77], v[178:181], v[130:133]
	v_mfma_f32_16x16x32_bf16 v[122:125], v[66:69], v[170:173], v[122:125]
	v_mfma_f32_16x16x32_bf16 v[114:117], v[74:77], v[170:173], v[114:117]
	v_mfma_f32_16x16x32_bf16 v[102:105], v[66:69], v[162:165], v[102:105]
	v_mfma_f32_16x16x32_bf16 v[98:101], v[74:77], v[162:165], v[98:101]
	v_mfma_f32_16x16x32_bf16 v[158:161], v[70:73], v[190:193], v[158:161]
	v_mfma_f32_16x16x32_bf16 v[154:157], v[78:81], v[190:193], v[154:157]
	v_mfma_f32_16x16x32_bf16 v[138:141], v[70:73], v[182:185], v[138:141]
	v_mfma_f32_16x16x32_bf16 v[130:133], v[78:81], v[182:185], v[130:133]
	v_mfma_f32_16x16x32_bf16 v[122:125], v[70:73], v[174:177], v[122:125]
	v_mfma_f32_16x16x32_bf16 v[114:117], v[78:81], v[174:177], v[114:117]
	v_mfma_f32_16x16x32_bf16 v[102:105], v[70:73], v[166:169], v[102:105]
	v_mfma_f32_16x16x32_bf16 v[98:101], v[78:81], v[166:169], v[98:101]
	s_setprio 0
	s_barrier
	s_mov_b32 m0, s64
	s_add_u32 s94, s52, 0x80000
	ds_read_b128 v[186:189], v231 offset:16384
	ds_read_b128 v[190:193], v231 offset:17408
	ds_read_b128 v[178:181], v231 offset:18432
	ds_read_b128 v[182:185], v231 offset:19456
	ds_read_b128 v[170:173], v231 offset:20480
	ds_read_b128 v[174:177], v231 offset:21504
	ds_read_b128 v[162:165], v231 offset:22528
	ds_read_b128 v[166:169], v231 offset:23552
	global_load_lds_dwordx4 v196, s[52:53]
	s_mov_b32 m0, s65
	s_addc_u32 s95, s53, 0
	global_load_lds_dwordx4 v200, s[52:53]
	s_mov_b32 m0, s66
	s_nop 0
	global_load_lds_dwordx4 v196, s[94:95]
	s_mov_b32 m0, s67
	s_andn2_b64 vcc, exec, s[56:57]
	global_load_lds_dwordx4 v200, s[94:95]
	s_mov_b32 m0, s68
	s_nop 0
	global_load_lds_dwordx4 v194, s[54:55]
	s_mov_b32 m0, s69
	s_nop 0
	global_load_lds_dwordx4 v198, s[54:55]
	s_cbranch_vccnz .LBB0_1232
	s_waitcnt vmcnt(24)
	s_cbranch_execnz .LBB0_1225
	s_branch .LBB0_1224

.LBB0_1383:
	s_add_u32 s6, s6, 0xe600000
	s_addc_u32 s7, s7, 0
	s_lshl_b32 s8, s8, 5
	s_add_i32 s52, s0, 0x18000
	s_and_b32 s17, s8, 0x60
	s_add_i32 s53, s52, s10
	s_mov_b64 s[8:9], 0x80
	s_lshl_b32 s16, s3, 13
	s_lshl_b32 s18, s17, 7
	v_lshl_add_u64 v[8:9], v[8:9], 0, s[8:9]
	s_mov_b32 m0, s53
	s_add_i32 s54, s53, 0x2000
	s_add_i32 s55, s48, 0x8000
	s_add_i32 s56, s48, 0xa000
	s_waitcnt vmcnt(2)
	s_barrier
	global_load_lds_dwordx4 v[8:9], off
	v_lshl_add_u64 v[6:7], v[6:7], 0, s[8:9]
	s_mov_b32 m0, s54
	s_add_u32 s14, s26, 0x160080
	global_load_lds_dwordx4 v[6:7], off
	v_lshl_add_u64 v[2:3], v[2:3], 0, s[8:9]
	s_mov_b32 m0, s55
	s_addc_u32 s15, s27, 0
	s_add_i32 s57, s0, 0x1c000
	global_load_lds_dwordx4 v[2:3], off
	v_lshl_add_u64 v[2:3], v[4:5], 0, s[8:9]
	s_mov_b32 m0, s56
	s_add_i32 s58, s57, s10
	global_load_lds_dwordx4 v[2:3], off
	v_lshl_add_u64 v[2:3], s[14:15], 0, v[198:199]
	s_mov_b32 m0, s58
	s_add_i32 s59, s58, 0x2000
	global_load_lds_dwordx4 v[2:3], off
	v_lshl_add_u64 v[2:3], s[14:15], 0, v[194:195]
	s_mov_b32 m0, s59
	s_cmpk_lt_u32 s1, 0x100
	global_load_lds_dwordx4 v[2:3], off
	v_lshrrev_b32_e32 v3, 1, v10
	v_and_b32_e32 v3, 24, v3
	v_and_b32_e32 v2, 15, v10
	v_lshlrev_b32_e32 v4, 1, v3
	v_lshl_or_b32 v1, s3, 6, v2
	v_lshl_or_b32 v2, v2, 6, v4
	v_lshlrev_b32_e32 v4, 2, v10
	v_and_b32_e32 v4, 32, v4
	v_bitop3_b32 v5, v2, s16, v4 bitop3:0xde
	v_bitop3_b32 v222, v2, s18, v4 bitop3:0xde
	v_add_u32_e32 v253, s52, v222
	v_add_u32_e32 v254, s57, v222
	v_or_b32_e32 v223, s17, v3
	v_lshrrev_b32_e32 v3, 1, v11
	v_mul_lo_u32 v2, v12, s2
	s_mov_b32 s1, 0x16000
	v_mad_u64_u32 v[2:3], s[16:17], v3, s1, v[2:3]
	v_or_b32_e32 v2, v2, v13
	s_mov_b64 s[14:15], 0x160080
	v_add_lshl_u32 v2, v2, v14, 1
	v_mov_b32_e32 v3, v199
	v_lshl_add_u64 v[202:203], v[2:3], 0, s[14:15]
	v_lshrrev_b32_e32 v3, 1, v16
	v_mul_lo_u32 v2, v15, s2
	v_mad_u64_u32 v[2:3], s[2:3], v3, s1, v[2:3]
	s_waitcnt vmcnt(6)
	v_or_b32_e32 v2, v2, v17
	v_add_lshl_u32 v2, v2, v18, 1
	v_mov_b32_e32 v3, v199
	s_sext_i32_i8 s69, s11
	s_cselect_b64 s[10:11], -1, 0
	s_ashr_i32 s60, s36, 31
	v_lshl_add_u64 v[204:205], v[2:3], 0, s[14:15]
	s_mov_b32 s24, 0
	v_mov_b64_e32 v[206:207], 0x240
	v_mov_b64_e32 v[208:209], 0x23f
	v_add_u32_e32 v224, s12, v222
	v_add_u32_e32 v225, s13, v222
	v_add_u32_e32 v226, s0, v5
	s_mov_b64 s[12:13], 0x80000
	s_mov_b32 s61, 0x80000
	s_mov_b64 s[14:15], 0x90000
	s_mov_b32 s62, 0x90000
	s_mov_b64 s[16:17], 0xa0000
	s_mov_b32 s63, 0xa0000
	s_mov_b64 s[18:19], 0xb0000
	s_mov_b32 s64, 0xb0000
	s_barrier
	s_branch .LBB0_1386

.LBB0_1397:
	s_waitcnt lgkmcnt(0)
	s_barrier
	s_setprio 1
	v_mfma_f32_16x16x32_bf16 v[62:65], v[146:149], v[186:189], v[62:65]
	v_mfma_f32_16x16x32_bf16 v[58:61], v[154:157], v[186:189], v[58:61]
	v_mfma_f32_16x16x32_bf16 v[54:57], v[146:149], v[178:181], v[54:57]
	v_mfma_f32_16x16x32_bf16 v[46:49], v[154:157], v[178:181], v[46:49]
	v_mfma_f32_16x16x32_bf16 v[38:41], v[146:149], v[170:173], v[38:41]
	v_mfma_f32_16x16x32_bf16 v[30:33], v[154:157], v[170:173], v[30:33]
	v_mfma_f32_16x16x32_bf16 v[22:25], v[146:149], v[162:165], v[22:25]
	v_mfma_f32_16x16x32_bf16 v[14:17], v[154:157], v[162:165], v[14:17]
	v_mfma_f32_16x16x32_bf16 v[62:65], v[150:153], v[190:193], v[62:65]
	v_mfma_f32_16x16x32_bf16 v[58:61], v[158:161], v[190:193], v[58:61]
	v_mfma_f32_16x16x32_bf16 v[54:57], v[150:153], v[182:185], v[54:57]
	v_mfma_f32_16x16x32_bf16 v[46:49], v[158:161], v[182:185], v[46:49]
	v_mfma_f32_16x16x32_bf16 v[38:41], v[150:153], v[174:177], v[38:41]
	v_mfma_f32_16x16x32_bf16 v[30:33], v[158:161], v[174:177], v[30:33]
	v_mfma_f32_16x16x32_bf16 v[22:25], v[150:153], v[166:169], v[22:25]
	v_mfma_f32_16x16x32_bf16 v[14:17], v[158:161], v[166:169], v[14:17]
	v_mfma_f32_16x16x32_bf16 v[50:53], v[130:133], v[186:189], v[50:53]
	v_mfma_f32_16x16x32_bf16 v[42:45], v[138:141], v[186:189], v[42:45]
	v_mfma_f32_16x16x32_bf16 v[34:37], v[130:133], v[178:181], v[34:37]
	v_mfma_f32_16x16x32_bf16 v[26:29], v[138:141], v[178:181], v[26:29]
	v_mfma_f32_16x16x32_bf16 v[18:21], v[130:133], v[170:173], v[18:21]
	v_mfma_f32_16x16x32_bf16 v[10:13], v[138:141], v[170:173], v[10:13]
	v_mfma_f32_16x16x32_bf16 v[6:9], v[130:133], v[162:165], v[6:9]
	v_mfma_f32_16x16x32_bf16 v[2:5], v[138:141], v[162:165], v[2:5]
	v_mfma_f32_16x16x32_bf16 v[50:53], v[134:137], v[190:193], v[50:53]
	v_mfma_f32_16x16x32_bf16 v[42:45], v[142:145], v[190:193], v[42:45]
	v_mfma_f32_16x16x32_bf16 v[34:37], v[134:137], v[182:185], v[34:37]
	v_mfma_f32_16x16x32_bf16 v[26:29], v[142:145], v[182:185], v[26:29]
	v_mfma_f32_16x16x32_bf16 v[18:21], v[134:137], v[174:177], v[18:21]
	v_mfma_f32_16x16x32_bf16 v[10:13], v[142:145], v[174:177], v[10:13]
	v_mfma_f32_16x16x32_bf16 v[6:9], v[134:137], v[166:169], v[6:9]
	v_mfma_f32_16x16x32_bf16 v[2:5], v[142:145], v[166:169], v[2:5]
	s_setprio 0
	s_barrier
	ds_read_b128 v[130:133], v253
	ds_read_b128 v[134:137], v253 offset:1024
	ds_read_b128 v[138:141], v253 offset:2048
	ds_read_b128 v[142:145], v253 offset:3072
	ds_read_b128 v[146:149], v254
	ds_read_b128 v[150:153], v254 offset:1024
	ds_read_b128 v[154:157], v254 offset:2048
	ds_read_b128 v[158:161], v254 offset:3072
	s_add_u32 s100, s30, 0x160000
	s_addc_u32 s101, s31, 0
	s_mov_b32 m0, s50
	ds_read_b128 v[162:165], v226 offset:32768
	ds_read_b128 v[166:169], v226 offset:33792
	ds_read_b128 v[170:173], v226 offset:34816
	ds_read_b128 v[174:177], v226 offset:35840
	ds_read_b128 v[178:181], v226 offset:36864
	ds_read_b128 v[182:185], v226 offset:37888
	ds_read_b128 v[186:189], v226 offset:38912
	ds_read_b128 v[190:193], v226 offset:39936
	global_load_lds_dwordx4 v200, s[100:101]
	s_mov_b32 m0, s51
	s_nop 0
	global_load_lds_dwordx4 v196, s[100:101]
	s_waitcnt lgkmcnt(0)
	s_barrier
	s_setprio 1
	v_mfma_f32_16x16x32_bf16 v[126:129], v[130:133], v[162:165], v[126:129]
	v_mfma_f32_16x16x32_bf16 v[122:125], v[138:141], v[162:165], v[122:125]
	v_mfma_f32_16x16x32_bf16 v[118:121], v[130:133], v[170:173], v[118:121]
	v_mfma_f32_16x16x32_bf16 v[110:113], v[138:141], v[170:173], v[110:113]
	v_mfma_f32_16x16x32_bf16 v[102:105], v[130:133], v[178:181], v[102:105]
	v_mfma_f32_16x16x32_bf16 v[94:97], v[138:141], v[178:181], v[94:97]
	v_mfma_f32_16x16x32_bf16 v[86:89], v[130:133], v[186:189], v[86:89]
	v_mfma_f32_16x16x32_bf16 v[78:81], v[138:141], v[186:189], v[78:81]
	v_mfma_f32_16x16x32_bf16 v[126:129], v[134:137], v[166:169], v[126:129]
	v_mfma_f32_16x16x32_bf16 v[122:125], v[142:145], v[166:169], v[122:125]
	v_mfma_f32_16x16x32_bf16 v[118:121], v[134:137], v[174:177], v[118:121]
	v_mfma_f32_16x16x32_bf16 v[110:113], v[142:145], v[174:177], v[110:113]
	v_mfma_f32_16x16x32_bf16 v[102:105], v[134:137], v[182:185], v[102:105]
	v_mfma_f32_16x16x32_bf16 v[94:97], v[142:145], v[182:185], v[94:97]
	v_mfma_f32_16x16x32_bf16 v[86:89], v[134:137], v[190:193], v[86:89]
	v_mfma_f32_16x16x32_bf16 v[78:81], v[142:145], v[190:193], v[78:81]
	v_mfma_f32_16x16x32_bf16 v[114:117], v[146:149], v[162:165], v[114:117]
	v_mfma_f32_16x16x32_bf16 v[106:109], v[154:157], v[162:165], v[106:109]
	v_mfma_f32_16x16x32_bf16 v[98:101], v[146:149], v[170:173], v[98:101]
	v_mfma_f32_16x16x32_bf16 v[90:93], v[154:157], v[170:173], v[90:93]
	v_mfma_f32_16x16x32_bf16 v[82:85], v[146:149], v[178:181], v[82:85]
	v_mfma_f32_16x16x32_bf16 v[74:77], v[154:157], v[178:181], v[74:77]
	v_mfma_f32_16x16x32_bf16 v[70:73], v[146:149], v[186:189], v[70:73]
	v_mfma_f32_16x16x32_bf16 v[66:69], v[154:157], v[186:189], v[66:69]
	v_mfma_f32_16x16x32_bf16 v[114:117], v[150:153], v[166:169], v[114:117]
	v_mfma_f32_16x16x32_bf16 v[106:109], v[158:161], v[166:169], v[106:109]
	v_mfma_f32_16x16x32_bf16 v[98:101], v[150:153], v[174:177], v[98:101]
	v_mfma_f32_16x16x32_bf16 v[90:93], v[158:161], v[174:177], v[90:93]
	v_mfma_f32_16x16x32_bf16 v[82:85], v[150:153], v[182:185], v[82:85]
	v_mfma_f32_16x16x32_bf16 v[74:77], v[158:161], v[182:185], v[74:77]
	v_mfma_f32_16x16x32_bf16 v[70:73], v[150:153], v[190:193], v[70:73]
	v_mfma_f32_16x16x32_bf16 v[66:69], v[158:161], v[190:193], v[66:69]
	s_setprio 0
	s_waitcnt vmcnt(8)
	s_barrier
	s_mov_b32 m0, s53
	ds_read_b128 v[162:165], v226 offset:49152
	ds_read_b128 v[166:169], v226 offset:50176
	ds_read_b128 v[170:173], v226 offset:51200
	ds_read_b128 v[174:177], v226 offset:52224
	ds_read_b128 v[178:181], v226 offset:53248
	ds_read_b128 v[182:185], v226 offset:54272
	ds_read_b128 v[186:189], v226 offset:55296
	ds_read_b128 v[190:193], v226 offset:56320
	s_add_u32 s98, s28, 0x80
	s_addc_u32 s99, s29, 0
	global_load_lds_dwordx4 v198, s[98:99]
	s_mov_b32 m0, s54
	s_nop 0
	global_load_lds_dwordx4 v194, s[98:99]
	s_mov_b32 m0, s58
	s_add_u32 s100, s74, 0x80
	s_addc_u32 s101, s75, 0
	global_load_lds_dwordx4 v198, s[100:101]
	s_mov_b32 m0, s59
	s_nop 0
	global_load_lds_dwordx4 v194, s[100:101]
	s_mov_b32 m0, s55
	s_add_u32 s98, s30, 0x80
	s_addc_u32 s99, s31, 0
	global_load_lds_dwordx4 v200, s[98:99]
	s_mov_b32 m0, s56
	s_nop 0
	global_load_lds_dwordx4 v196, s[98:99]
	s_waitcnt lgkmcnt(0)
	s_barrier
	s_setprio 1
	v_mfma_f32_16x16x32_bf16 v[62:65], v[130:133], v[162:165], v[62:65]
	v_mfma_f32_16x16x32_bf16 v[58:61], v[138:141], v[162:165], v[58:61]
	v_mfma_f32_16x16x32_bf16 v[54:57], v[130:133], v[170:173], v[54:57]
	v_mfma_f32_16x16x32_bf16 v[46:49], v[138:141], v[170:173], v[46:49]
	v_mfma_f32_16x16x32_bf16 v[38:41], v[130:133], v[178:181], v[38:41]
	v_mfma_f32_16x16x32_bf16 v[30:33], v[138:141], v[178:181], v[30:33]
	v_mfma_f32_16x16x32_bf16 v[22:25], v[130:133], v[186:189], v[22:25]
	v_mfma_f32_16x16x32_bf16 v[14:17], v[138:141], v[186:189], v[14:17]
	v_mfma_f32_16x16x32_bf16 v[62:65], v[134:137], v[166:169], v[62:65]
	v_mfma_f32_16x16x32_bf16 v[58:61], v[142:145], v[166:169], v[58:61]
	v_mfma_f32_16x16x32_bf16 v[54:57], v[134:137], v[174:177], v[54:57]
	v_mfma_f32_16x16x32_bf16 v[46:49], v[142:145], v[174:177], v[46:49]
	v_mfma_f32_16x16x32_bf16 v[38:41], v[134:137], v[182:185], v[38:41]
	v_mfma_f32_16x16x32_bf16 v[30:33], v[142:145], v[182:185], v[30:33]
	v_mfma_f32_16x16x32_bf16 v[22:25], v[134:137], v[190:193], v[22:25]
	v_mfma_f32_16x16x32_bf16 v[14:17], v[142:145], v[190:193], v[14:17]
	v_mfma_f32_16x16x32_bf16 v[50:53], v[146:149], v[162:165], v[50:53]
	v_mfma_f32_16x16x32_bf16 v[42:45], v[154:157], v[162:165], v[42:45]
	v_mfma_f32_16x16x32_bf16 v[34:37], v[146:149], v[170:173], v[34:37]
	v_mfma_f32_16x16x32_bf16 v[26:29], v[154:157], v[170:173], v[26:29]
	v_mfma_f32_16x16x32_bf16 v[18:21], v[146:149], v[178:181], v[18:21]
	v_mfma_f32_16x16x32_bf16 v[10:13], v[154:157], v[178:181], v[10:13]
	v_mfma_f32_16x16x32_bf16 v[6:9], v[146:149], v[186:189], v[6:9]
	v_mfma_f32_16x16x32_bf16 v[2:5], v[154:157], v[186:189], v[2:5]
	v_mfma_f32_16x16x32_bf16 v[50:53], v[150:153], v[166:169], v[50:53]
	v_mfma_f32_16x16x32_bf16 v[42:45], v[158:161], v[166:169], v[42:45]
	v_mfma_f32_16x16x32_bf16 v[34:37], v[150:153], v[174:177], v[34:37]
	v_mfma_f32_16x16x32_bf16 v[26:29], v[158:161], v[174:177], v[26:29]
	v_mfma_f32_16x16x32_bf16 v[18:21], v[150:153], v[182:185], v[18:21]
	v_mfma_f32_16x16x32_bf16 v[10:13], v[158:161], v[182:185], v[10:13]
	v_mfma_f32_16x16x32_bf16 v[6:9], v[150:153], v[190:193], v[6:9]
	v_mfma_f32_16x16x32_bf16 v[2:5], v[158:161], v[190:193], v[2:5]
	s_setprio 0
	s_waitcnt vmcnt(8)
	s_barrier
	s_add_i32 s72, s72, 2
	s_add_u32 s26, s26, 0x100
	s_addc_u32 s27, s27, 0
	s_cmpk_gt_u32 s72, 0x55
	s_cbranch_scc1 .LBB0_1405

.LBB0_1401:
	s_add_u32 s28, s22, s26
	s_addc_u32 s29, s23, s27
	s_add_u32 s28, s28, 0x100
	s_addc_u32 s29, s29, 0
	s_add_u32 s73, s70, s26
	s_addc_u32 s74, s71, s27
	s_waitcnt lgkmcnt(0)
	s_cmpk_eq_i32 s26, 0x2b00
	s_cselect_b32 s31, s1, s29
	s_cselect_b32 s30, s0, s28
	s_cselect_b32 s29, s21, s74
	s_cselect_b32 s28, s20, s73
	s_barrier
	s_setprio 1
	s_waitcnt lgkmcnt(0)
	v_mfma_f32_16x16x32_bf16 v[126:129], v[146:149], v[186:189], v[126:129]
	v_mfma_f32_16x16x32_bf16 v[122:125], v[154:157], v[186:189], v[122:125]
	v_mfma_f32_16x16x32_bf16 v[118:121], v[146:149], v[178:181], v[118:121]
	v_mfma_f32_16x16x32_bf16 v[110:113], v[154:157], v[178:181], v[110:113]
	v_mfma_f32_16x16x32_bf16 v[102:105], v[146:149], v[170:173], v[102:105]
	v_mfma_f32_16x16x32_bf16 v[94:97], v[154:157], v[170:173], v[94:97]
	v_mfma_f32_16x16x32_bf16 v[86:89], v[146:149], v[162:165], v[86:89]
	v_mfma_f32_16x16x32_bf16 v[78:81], v[154:157], v[162:165], v[78:81]
	v_mfma_f32_16x16x32_bf16 v[126:129], v[150:153], v[190:193], v[126:129]
	v_mfma_f32_16x16x32_bf16 v[122:125], v[158:161], v[190:193], v[122:125]
	v_mfma_f32_16x16x32_bf16 v[118:121], v[150:153], v[182:185], v[118:121]
	v_mfma_f32_16x16x32_bf16 v[110:113], v[158:161], v[182:185], v[110:113]
	v_mfma_f32_16x16x32_bf16 v[102:105], v[150:153], v[174:177], v[102:105]
	v_mfma_f32_16x16x32_bf16 v[94:97], v[158:161], v[174:177], v[94:97]
	v_mfma_f32_16x16x32_bf16 v[86:89], v[150:153], v[166:169], v[86:89]
	v_mfma_f32_16x16x32_bf16 v[78:81], v[158:161], v[166:169], v[78:81]
	v_mfma_f32_16x16x32_bf16 v[114:117], v[130:133], v[186:189], v[114:117]
	v_mfma_f32_16x16x32_bf16 v[106:109], v[138:141], v[186:189], v[106:109]
	v_mfma_f32_16x16x32_bf16 v[98:101], v[130:133], v[178:181], v[98:101]
	v_mfma_f32_16x16x32_bf16 v[90:93], v[138:141], v[178:181], v[90:93]
	v_mfma_f32_16x16x32_bf16 v[82:85], v[130:133], v[170:173], v[82:85]
	v_mfma_f32_16x16x32_bf16 v[74:77], v[138:141], v[170:173], v[74:77]
	v_mfma_f32_16x16x32_bf16 v[70:73], v[130:133], v[162:165], v[70:73]
	v_mfma_f32_16x16x32_bf16 v[66:69], v[138:141], v[162:165], v[66:69]
	v_mfma_f32_16x16x32_bf16 v[114:117], v[134:137], v[190:193], v[114:117]
	v_mfma_f32_16x16x32_bf16 v[106:109], v[142:145], v[190:193], v[106:109]
	v_mfma_f32_16x16x32_bf16 v[98:101], v[134:137], v[182:185], v[98:101]
	v_mfma_f32_16x16x32_bf16 v[90:93], v[142:145], v[182:185], v[90:93]
	v_mfma_f32_16x16x32_bf16 v[82:85], v[134:137], v[174:177], v[82:85]
	v_mfma_f32_16x16x32_bf16 v[74:77], v[142:145], v[174:177], v[74:77]
	v_mfma_f32_16x16x32_bf16 v[70:73], v[134:137], v[166:169], v[70:73]
	v_mfma_f32_16x16x32_bf16 v[66:69], v[142:145], v[166:169], v[66:69]
	s_setprio 0
	s_barrier
	s_mov_b32 m0, s44
	s_add_u32 s74, s28, 0x160000
	ds_read_b128 v[186:189], v226 offset:16384
	ds_read_b128 v[190:193], v226 offset:17408
	ds_read_b128 v[178:181], v226 offset:18432
	ds_read_b128 v[182:185], v226 offset:19456
	ds_read_b128 v[170:173], v226 offset:20480
	ds_read_b128 v[174:177], v226 offset:21504
	ds_read_b128 v[162:165], v226 offset:22528
	ds_read_b128 v[166:169], v226 offset:23552
	global_load_lds_dwordx4 v198, s[28:29]
	s_mov_b32 m0, s45
	s_addc_u32 s75, s29, 0
	global_load_lds_dwordx4 v194, s[28:29]
	s_mov_b32 m0, s46
	s_nop 0
	global_load_lds_dwordx4 v198, s[74:75]
	s_mov_b32 m0, s47
	s_andn2_b64 vcc, exec, s[34:35]
	global_load_lds_dwordx4 v194, s[74:75]
	s_mov_b32 m0, s48
	s_nop 0
	global_load_lds_dwordx4 v200, s[30:31]
	s_mov_b32 m0, s49
	s_nop 0
	global_load_lds_dwordx4 v196, s[30:31]
	s_cbranch_vccnz .LBB0_1404
	s_waitcnt vmcnt(24)
	s_cbranch_execnz .LBB0_1397
	s_branch .LBB0_1396

.LBB0_1578:
	s_add_i32 s53, s16, 0x18000
	s_and_b32 s2, s2, 3
	s_add_i32 s54, s53, s17
	s_mov_b64 s[12:13], 0x80
	s_lshl_b32 s5, s15, 13
	s_lshl_b32 s20, s2, 12
	v_lshl_add_u64 v[8:9], v[8:9], 0, s[12:13]
	s_mov_b32 m0, s54
	s_add_i32 s55, s54, 0x2000
	s_add_i32 s56, s49, 0x8000
	s_add_i32 s57, s49, 0xa000
	s_waitcnt vmcnt(2)
	s_barrier
	global_load_lds_dwordx4 v[8:9], off
	v_lshl_add_u64 v[6:7], v[6:7], 0, s[12:13]
	s_mov_b32 m0, s55
	s_add_u32 s18, s30, 0x40080
	global_load_lds_dwordx4 v[6:7], off
	v_lshl_add_u64 v[2:3], v[2:3], 0, s[12:13]
	s_mov_b32 m0, s56
	s_addc_u32 s19, s31, 0
	s_add_i32 s58, s16, 0x1c000
	global_load_lds_dwordx4 v[2:3], off
	v_lshl_add_u64 v[2:3], v[4:5], 0, s[12:13]
	s_mov_b32 m0, s57
	s_add_i32 s59, s58, s17
	global_load_lds_dwordx4 v[2:3], off
	v_lshl_add_u64 v[2:3], s[18:19], 0, v[196:197]
	s_mov_b32 m0, s59
	s_add_i32 s60, s59, 0x2000
	global_load_lds_dwordx4 v[2:3], off
	v_lshl_add_u64 v[2:3], s[18:19], 0, v[200:201]
	s_mov_b32 m0, s60
	s_mov_b64 s[18:19], 0x17600000
	global_load_lds_dwordx4 v[2:3], off
	v_bfe_u32 v3, v10, 4, 2
	v_and_b32_e32 v2, 15, v10
	v_lshlrev_b32_e32 v4, 3, v3
	v_lshlrev_b32_e32 v3, 4, v3
	v_lshl_or_b32 v1, s15, 6, v2
	v_lshl_or_b32 v2, v2, 6, v3
	v_lshlrev_b32_e32 v3, 2, v10
	v_and_b32_e32 v3, 32, v3
	v_bitop3_b32 v5, v2, s5, v3 bitop3:0xde
	v_bitop3_b32 v205, v2, s20, v3 bitop3:0xde
	v_add_u32_e32 v253, s53, v205
	v_add_u32_e32 v254, s58, v205
	v_bfe_i32 v2, v10, 4, 1
	v_lshlrev_b32_e32 v202, 1, v3
	v_and_b32_e32 v206, 24, v2
	v_lshl_add_u64 v[2:3], s[8:9], 0, v[202:203]
	v_lshl_add_u64 v[208:209], v[2:3], 0, s[18:19]
	v_lshrrev_b32_e32 v3, 1, v15
	v_mul_lo_u32 v2, v17, s0
	s_mov_b32 s63, 0x53000
	v_mad_u64_u32 v[2:3], s[18:19], v3, s63, v[2:3]
	v_or_b32_e32 v2, v2, v16
	v_add_lshl_u32 v202, v2, v18, 1
	v_lshrrev_b32_e32 v3, 1, v11
	v_mul_lo_u32 v2, v12, s0
	v_mad_u64_u32 v[2:3], s[20:21], v3, s63, v[2:3]
	s_waitcnt vmcnt(6)
	s_mov_b64 s[18:19], 0x530080
	v_or_b32_e32 v2, v2, v13
	s_cmpk_lt_u32 s14, 0x100
	v_lshl_add_u64 v[210:211], v[202:203], 0, s[18:19]
	v_add_lshl_u32 v202, v2, v14, 1
	s_cselect_b64 s[14:15], -1, 0
	v_lshl_or_b32 v231, s2, 6, v4
	v_and_b32_e32 v204, 8, v10
	s_mov_b32 s34, 0
	v_mov_b32_e32 v207, v203
	s_ashr_i32 s61, s33, 31
	s_ashr_i32 s62, s40, 31
	v_lshl_add_u64 v[212:213], v[202:203], 0, s[18:19]
	v_mov_b64_e32 v[214:215], 0x1388
	v_mov_b64_e32 v[216:217], 0x1387
	s_movk_i32 s64, 0x272
	v_add_u32_e32 v232, s1, v205
	v_add_u32_e32 v233, s3, v205
	v_add_u32_e32 v234, s16, v5
	v_mov_b32_e32 v235, 0x7f7f7f7f
	s_movk_i32 s65, 0x163f
	s_movk_i32 s66, 0x1e3f
	s_movk_i32 s67, 0x2640
	s_movk_i32 s68, 0x1800
	s_movk_i32 s69, 0x800
	s_movk_i32 s70, 0x1a00
	s_mov_b32 s71, 0xa600
	s_movk_i32 s72, 0x200
	s_mov_b64 s[16:17], 0x460fe9c0
	s_movk_i32 s73, 0xf7ff
	s_mov_b64 s[18:19], 0x12dfe1c0
	s_mov_b64 s[20:21], 0x151fcfc0
	s_mov_b64 s[22:23], 0x17603240
	s_movk_i32 s74, 0xf00
	v_mov_b32_e32 v236, 0x3c800000
	v_mov_b32_e32 v237, 0xbcb8aa3b
	v_mov_b32_e32 v238, 0x800
	v_mov_b32_e32 v239, 0xa600
	v_mov_b32_e32 v240, 0x200
	s_barrier
	s_branch .LBB0_1581

.LBB0_2208:
	s_add_u32 s44, s12, 0x17600000
	s_addc_u32 s45, s13, 0
	s_add_u32 s10, s12, 0xe600000
	s_addc_u32 s11, s13, 0
	s_add_u32 s46, s12, 0x17606480
	s_addc_u32 s47, s13, 0
	s_add_u32 s12, s12, 0x12e00000
	s_addc_u32 s13, s13, 0
	s_lshl_b32 s14, s14, 5
	s_add_i32 s48, s20, 0x18000
	s_and_b32 s25, s14, 0x60
	s_add_i32 s49, s48, s19
	s_mov_b64 s[14:15], 0x80
	s_lshl_b32 s24, s0, 13
	s_lshl_b32 s26, s25, 7
	v_lshl_add_u64 v[8:9], v[8:9], 0, s[14:15]
	s_mov_b32 m0, s49
	s_add_i32 s50, s49, 0x2000
	s_add_i32 s51, s40, 0x8000
	s_add_i32 s52, s40, 0xa000
	s_waitcnt vmcnt(2)
	s_barrier
	global_load_lds_dwordx4 v[8:9], off
	v_lshl_add_u64 v[6:7], v[6:7], 0, s[14:15]
	s_mov_b32 m0, s50
	s_mov_b64 s[16:17], 0x100
	s_add_u32 s22, s6, 0x40080
	global_load_lds_dwordx4 v[6:7], off
	v_lshl_add_u64 v[2:3], v[2:3], 0, s[16:17]
	s_mov_b32 m0, s51
	s_addc_u32 s23, s7, 0
	s_add_i32 s53, s20, 0x1c000
	global_load_lds_dwordx4 v[2:3], off
	v_lshl_add_u64 v[2:3], v[4:5], 0, s[16:17]
	s_mov_b32 m0, s52
	s_add_i32 s54, s53, s19
	global_load_lds_dwordx4 v[2:3], off
	v_lshl_add_u64 v[2:3], s[22:23], 0, v[196:197]
	s_mov_b32 m0, s54
	s_add_i32 s55, s54, 0x2000
	global_load_lds_dwordx4 v[2:3], off
	v_lshl_add_u64 v[2:3], s[22:23], 0, v[200:201]
	s_mov_b32 m0, s55
	s_cmpk_lt_u32 s18, 0x100
	global_load_lds_dwordx4 v[2:3], off
	v_lshrrev_b32_e32 v3, 1, v10
	v_and_b32_e32 v3, 24, v3
	v_and_b32_e32 v2, 15, v10
	v_lshlrev_b32_e32 v4, 1, v3
	v_lshl_or_b32 v1, s0, 6, v2
	v_lshl_or_b32 v2, v2, 6, v4
	v_lshlrev_b32_e32 v4, 2, v10
	v_and_b32_e32 v4, 32, v4
	v_bitop3_b32 v5, v2, s24, v4 bitop3:0xde
	v_bitop3_b32 v222, v2, s26, v4 bitop3:0xde
	v_add_u32_e32 v253, s48, v222
	v_add_u32_e32 v254, s53, v222
	v_or_b32_e32 v223, s25, v3
	v_lshrrev_b32_e32 v3, 1, v15
	v_mul_lo_u32 v2, v17, s1
	s_mov_b32 s0, 0x53000
	v_mad_u64_u32 v[2:3], s[22:23], v3, s0, v[2:3]
	v_or_b32_e32 v2, v2, v16
	v_add_lshl_u32 v2, v2, v18, 1
	v_mov_b32_e32 v3, v197
	s_mov_b64 s[22:23], 0x530100
	v_lshl_add_u64 v[202:203], v[2:3], 0, s[22:23]
	v_lshrrev_b32_e32 v3, 1, v11
	v_mul_lo_u32 v2, v12, s1
	v_mad_u64_u32 v[2:3], s[0:1], v3, s0, v[2:3]
	s_waitcnt vmcnt(6)
	v_or_b32_e32 v2, v2, v13
	v_add_lshl_u32 v2, v2, v14, 1
	v_mov_b32_e32 v3, v197
	s_cselect_b64 s[18:19], -1, 0
	s_ashr_i32 s56, s33, 31
	v_lshl_add_u64 v[204:205], v[2:3], 0, s[22:23]
	s_mov_b32 s62, 0
	v_mov_b64_e32 v[206:207], 0x200
	v_mov_b64_e32 v[208:209], 0x1ff
	v_add_u32_e32 v224, s2, v222
	v_add_u32_e32 v225, s3, v222
	v_add_u32_e32 v226, s20, v5
	v_mov_b32_e32 v227, 0x7f7f7f7f
	s_mov_b32 s57, 0xa600
	s_mov_b32 s20, 0x3a800000
	s_mov_b32 s26, 0
	s_barrier
	s_branch .LBB0_2211

.LBB0_2224:
	s_waitcnt lgkmcnt(0)
	s_barrier
	s_setprio 1
	v_mfma_f32_16x16x128_f8f6f4 v[126:129], v[26:33], v[58:65], v[126:129]
	v_mfma_f32_16x16x128_f8f6f4 v[122:125], v[18:25], v[58:65], v[122:125]
	v_mfma_f32_16x16x128_f8f6f4 v[110:113], v[26:33], v[50:57], v[110:113]
	v_mfma_f32_16x16x128_f8f6f4 v[106:109], v[18:25], v[50:57], v[106:109]
	v_mfma_f32_16x16x128_f8f6f4 v[94:97], v[26:33], v[42:49], v[94:97]
	v_mfma_f32_16x16x128_f8f6f4 v[90:93], v[18:25], v[42:49], v[90:93]
	v_mfma_f32_16x16x128_f8f6f4 v[78:81], v[26:33], v[34:41], v[78:81]
	v_mfma_f32_16x16x128_f8f6f4 v[74:77], v[18:25], v[34:41], v[74:77]
	v_mfma_f32_16x16x128_f8f6f4 v[118:121], v[10:17], v[58:65], v[118:121]
	v_mfma_f32_16x16x128_f8f6f4 v[114:117], v[2:9], v[58:65], v[114:117]
	v_mfma_f32_16x16x128_f8f6f4 v[102:105], v[10:17], v[50:57], v[102:105]
	v_mfma_f32_16x16x128_f8f6f4 v[98:101], v[2:9], v[50:57], v[98:101]
	v_mfma_f32_16x16x128_f8f6f4 v[86:89], v[10:17], v[42:49], v[86:89]
	v_mfma_f32_16x16x128_f8f6f4 v[82:85], v[2:9], v[42:49], v[82:85]
	v_mfma_f32_16x16x128_f8f6f4 v[70:73], v[10:17], v[34:41], v[70:73]
	v_mfma_f32_16x16x128_f8f6f4 v[66:69], v[2:9], v[34:41], v[66:69]
	s_setprio 0
	s_barrier
	ds_read_b128 v[2:5], v253
	ds_read_b128 v[6:9], v253 offset:1024
	ds_read_b128 v[10:13], v253 offset:2048
	ds_read_b128 v[14:17], v253 offset:3072
	ds_read_b128 v[18:21], v254
	ds_read_b128 v[22:25], v254 offset:1024
	ds_read_b128 v[26:29], v254 offset:2048
	ds_read_b128 v[30:33], v254 offset:3072
	s_add_u32 s100, s28, 0x530000
	s_addc_u32 s101, s29, 0
	s_mov_b32 m0, s42
	ds_read_b128 v[34:37], v226 offset:32768
	ds_read_b128 v[38:41], v226 offset:33792
	ds_read_b128 v[42:45], v226 offset:34816
	ds_read_b128 v[46:49], v226 offset:35840
	ds_read_b128 v[50:53], v226 offset:36864
	ds_read_b128 v[54:57], v226 offset:37888
	ds_read_b128 v[58:61], v226 offset:38912
	ds_read_b128 v[62:65], v226 offset:39936
	global_load_lds_dwordx4 v194, s[100:101]
	s_mov_b32 m0, s43
	s_nop 0
	global_load_lds_dwordx4 v198, s[100:101]
	s_waitcnt lgkmcnt(0)
	s_barrier
	s_setprio 1
	v_mfma_f32_16x16x128_f8f6f4 v[190:193], v[2:9], v[34:41], v[190:193]
	v_mfma_f32_16x16x128_f8f6f4 v[186:189], v[10:17], v[34:41], v[186:189]
	v_mfma_f32_16x16x128_f8f6f4 v[174:177], v[2:9], v[42:49], v[174:177]
	v_mfma_f32_16x16x128_f8f6f4 v[170:173], v[10:17], v[42:49], v[170:173]
	v_mfma_f32_16x16x128_f8f6f4 v[158:161], v[2:9], v[50:57], v[158:161]
	v_mfma_f32_16x16x128_f8f6f4 v[154:157], v[10:17], v[50:57], v[154:157]
	v_mfma_f32_16x16x128_f8f6f4 v[142:145], v[2:9], v[58:65], v[142:145]
	v_mfma_f32_16x16x128_f8f6f4 v[138:141], v[10:17], v[58:65], v[138:141]
	v_mfma_f32_16x16x128_f8f6f4 v[182:185], v[18:25], v[34:41], v[182:185]
	v_mfma_f32_16x16x128_f8f6f4 v[178:181], v[26:33], v[34:41], v[178:181]
	v_mfma_f32_16x16x128_f8f6f4 v[166:169], v[18:25], v[42:49], v[166:169]
	v_mfma_f32_16x16x128_f8f6f4 v[162:165], v[26:33], v[42:49], v[162:165]
	v_mfma_f32_16x16x128_f8f6f4 v[150:153], v[18:25], v[50:57], v[150:153]
	v_mfma_f32_16x16x128_f8f6f4 v[146:149], v[26:33], v[50:57], v[146:149]
	v_mfma_f32_16x16x128_f8f6f4 v[134:137], v[18:25], v[58:65], v[134:137]
	v_mfma_f32_16x16x128_f8f6f4 v[130:133], v[26:33], v[58:65], v[130:133]
	s_setprio 0
	s_waitcnt vmcnt(8)
	s_barrier
	s_mov_b32 m0, s49
	ds_read_b128 v[34:37], v226 offset:49152
	ds_read_b128 v[38:41], v226 offset:50176
	ds_read_b128 v[42:45], v226 offset:51200
	ds_read_b128 v[46:49], v226 offset:52224
	ds_read_b128 v[50:53], v226 offset:53248
	ds_read_b128 v[54:57], v226 offset:54272
	ds_read_b128 v[58:61], v226 offset:55296
	ds_read_b128 v[62:65], v226 offset:56320
	s_add_u32 s98, s26, 0x80
	s_addc_u32 s99, s27, 0
	global_load_lds_dwordx4 v196, s[98:99]
	s_mov_b32 m0, s50
	s_nop 0
	global_load_lds_dwordx4 v200, s[98:99]
	s_mov_b32 m0, s54
	s_add_u32 s100, s70, 0x80
	s_addc_u32 s101, s71, 0
	global_load_lds_dwordx4 v196, s[100:101]
	s_mov_b32 m0, s55
	s_nop 0
	global_load_lds_dwordx4 v200, s[100:101]
	s_mov_b32 m0, s51
	s_add_u32 s98, s28, 0x100
	s_addc_u32 s99, s29, 0
	global_load_lds_dwordx4 v194, s[98:99]
	s_mov_b32 m0, s52
	s_nop 0
	global_load_lds_dwordx4 v198, s[98:99]
	s_waitcnt lgkmcnt(0)
	s_barrier
	s_setprio 1
	v_mfma_f32_16x16x128_f8f6f4 v[126:129], v[2:9], v[34:41], v[126:129]
	v_mfma_f32_16x16x128_f8f6f4 v[122:125], v[10:17], v[34:41], v[122:125]
	v_mfma_f32_16x16x128_f8f6f4 v[110:113], v[2:9], v[42:49], v[110:113]
	v_mfma_f32_16x16x128_f8f6f4 v[106:109], v[10:17], v[42:49], v[106:109]
	v_mfma_f32_16x16x128_f8f6f4 v[94:97], v[2:9], v[50:57], v[94:97]
	v_mfma_f32_16x16x128_f8f6f4 v[90:93], v[10:17], v[50:57], v[90:93]
	v_mfma_f32_16x16x128_f8f6f4 v[78:81], v[2:9], v[58:65], v[78:81]
	v_mfma_f32_16x16x128_f8f6f4 v[74:77], v[10:17], v[58:65], v[74:77]
	v_mfma_f32_16x16x128_f8f6f4 v[118:121], v[18:25], v[34:41], v[118:121]
	v_mfma_f32_16x16x128_f8f6f4 v[114:117], v[26:33], v[34:41], v[114:117]
	v_mfma_f32_16x16x128_f8f6f4 v[102:105], v[18:25], v[42:49], v[102:105]
	v_mfma_f32_16x16x128_f8f6f4 v[98:101], v[26:33], v[42:49], v[98:101]
	v_mfma_f32_16x16x128_f8f6f4 v[86:89], v[18:25], v[50:57], v[86:89]
	v_mfma_f32_16x16x128_f8f6f4 v[82:85], v[26:33], v[50:57], v[82:85]
	v_mfma_f32_16x16x128_f8f6f4 v[70:73], v[18:25], v[58:65], v[70:73]
	v_mfma_f32_16x16x128_f8f6f4 v[66:69], v[26:33], v[58:65], v[66:69]
	s_setprio 0
	s_waitcnt vmcnt(8)
	s_barrier
	s_add_i32 s69, s69, 2
	s_add_u32 s6, s6, 0x200
	s_addc_u32 s7, s7, 0
	s_add_u32 s67, s67, 0x100
	s_addc_u32 s68, s68, 0
	s_cmp_gt_u32 s69, 13
	s_cbranch_scc1 .LBB0_2232

.LBB0_2228:
	s_add_u32 s26, s4, s6
	s_addc_u32 s27, s5, s7
	s_add_u32 s26, s26, 0x200
	s_addc_u32 s27, s27, 0
	s_waitcnt lgkmcnt(0)
	s_cmpk_eq_i32 s6, 0xe00
	s_cselect_b32 s29, s23, s27
	s_cselect_b32 s28, s22, s26
	s_cselect_b32 s27, s65, s68
	s_cselect_b32 s26, s66, s67
	s_barrier
	s_setprio 1
	s_waitcnt lgkmcnt(0)
	v_mfma_f32_16x16x128_f8f6f4 v[190:193], v[26:33], v[58:65], v[190:193]
	v_mfma_f32_16x16x128_f8f6f4 v[186:189], v[18:25], v[58:65], v[186:189]
	v_mfma_f32_16x16x128_f8f6f4 v[174:177], v[26:33], v[50:57], v[174:177]
	v_mfma_f32_16x16x128_f8f6f4 v[170:173], v[18:25], v[50:57], v[170:173]
	v_mfma_f32_16x16x128_f8f6f4 v[158:161], v[26:33], v[42:49], v[158:161]
	v_mfma_f32_16x16x128_f8f6f4 v[154:157], v[18:25], v[42:49], v[154:157]
	v_mfma_f32_16x16x128_f8f6f4 v[142:145], v[26:33], v[34:41], v[142:145]
	v_mfma_f32_16x16x128_f8f6f4 v[138:141], v[18:25], v[34:41], v[138:141]
	v_mfma_f32_16x16x128_f8f6f4 v[182:185], v[10:17], v[58:65], v[182:185]
	v_mfma_f32_16x16x128_f8f6f4 v[178:181], v[2:9], v[58:65], v[178:181]
	v_mfma_f32_16x16x128_f8f6f4 v[166:169], v[10:17], v[50:57], v[166:169]
	v_mfma_f32_16x16x128_f8f6f4 v[162:165], v[2:9], v[50:57], v[162:165]
	v_mfma_f32_16x16x128_f8f6f4 v[150:153], v[10:17], v[42:49], v[150:153]
	v_mfma_f32_16x16x128_f8f6f4 v[146:149], v[2:9], v[42:49], v[146:149]
	v_mfma_f32_16x16x128_f8f6f4 v[134:137], v[10:17], v[34:41], v[134:137]
	v_mfma_f32_16x16x128_f8f6f4 v[130:133], v[2:9], v[34:41], v[130:133]
	s_setprio 0
	s_barrier
	s_mov_b32 m0, s36
	s_add_u32 s70, s26, 0x40000
	ds_read_b128 v[58:61], v226 offset:16384
	ds_read_b128 v[62:65], v226 offset:17408
	ds_read_b128 v[50:53], v226 offset:18432
	ds_read_b128 v[54:57], v226 offset:19456
	ds_read_b128 v[42:45], v226 offset:20480
	ds_read_b128 v[46:49], v226 offset:21504
	ds_read_b128 v[34:37], v226 offset:22528
	ds_read_b128 v[38:41], v226 offset:23552
	global_load_lds_dwordx4 v196, s[26:27]
	s_mov_b32 m0, s37
	s_addc_u32 s71, s27, 0
	global_load_lds_dwordx4 v200, s[26:27]
	s_mov_b32 m0, s38
	s_nop 0
	global_load_lds_dwordx4 v196, s[70:71]
	s_mov_b32 m0, s39
	s_andn2_b64 vcc, exec, s[30:31]
	global_load_lds_dwordx4 v200, s[70:71]
	s_mov_b32 m0, s40
	s_nop 0
	global_load_lds_dwordx4 v194, s[28:29]
	s_mov_b32 m0, s41
	s_nop 0
	global_load_lds_dwordx4 v198, s[28:29]
	s_cbranch_vccnz .LBB0_2231
	s_waitcnt vmcnt(24)
	s_cbranch_execnz .LBB0_2224
	s_branch .LBB0_2223

.LBB0_2395:
	s_add_u32 s4, s4, 0x17600000
	s_addc_u32 s5, s5, 0
	s_lshl_b32 s6, s6, 5
	s_add_i32 s57, s3, 0x18000
	s_and_b32 s17, s6, 0x60
	s_add_i32 s58, s57, s13
	s_mov_b64 s[6:7], 0x80
	s_lshl_b32 s16, s9, 13
	s_lshl_b32 s18, s17, 7
	v_lshl_add_u64 v[8:9], v[8:9], 0, s[6:7]
	s_mov_b32 m0, s58
	s_add_i32 s59, s58, 0x2000
	s_add_i32 s60, s53, 0x8000
	s_add_i32 s61, s53, 0xa000
	s_waitcnt vmcnt(2)
	s_barrier
	global_load_lds_dwordx4 v[8:9], off
	v_lshl_add_u64 v[6:7], v[6:7], 0, s[6:7]
	s_mov_b32 m0, s59
	s_add_u32 s14, s36, 0x40080
	global_load_lds_dwordx4 v[6:7], off
	v_lshl_add_u64 v[2:3], v[2:3], 0, s[6:7]
	s_mov_b32 m0, s60
	s_addc_u32 s15, s37, 0
	s_add_i32 s62, s3, 0x1c000
	global_load_lds_dwordx4 v[2:3], off
	v_lshl_add_u64 v[2:3], v[4:5], 0, s[6:7]
	s_mov_b32 m0, s61
	s_add_i32 s63, s62, s13
	global_load_lds_dwordx4 v[2:3], off
	v_lshl_add_u64 v[2:3], s[14:15], 0, v[196:197]
	s_mov_b32 m0, s63
	s_add_i32 s64, s63, 0x2000
	global_load_lds_dwordx4 v[2:3], off
	v_lshl_add_u64 v[2:3], s[14:15], 0, v[200:201]
	s_mov_b32 m0, s64
	s_mov_b64 s[14:15], 0x40080
	global_load_lds_dwordx4 v[2:3], off
	v_lshrrev_b32_e32 v3, 1, v10
	v_and_b32_e32 v3, 24, v3
	v_and_b32_e32 v2, 15, v10
	v_lshlrev_b32_e32 v4, 1, v3
	v_lshl_or_b32 v1, s9, 6, v2
	v_lshl_or_b32 v2, v2, 6, v4
	v_lshlrev_b32_e32 v4, 2, v10
	v_and_b32_e32 v4, 32, v4
	v_bitop3_b32 v5, v2, s16, v4 bitop3:0xde
	v_bitop3_b32 v222, v2, s18, v4 bitop3:0xde
	v_add_u32_e32 v253, s57, v222
	v_add_u32_e32 v254, s62, v222
	v_lshlrev_b32_e32 v2, 14, v14
	v_and_b32_e32 v2, 0xffff8000, v2
	v_or_b32_e32 v223, s17, v3
	v_lshl_add_u32 v2, v15, 11, v2
	v_and_b32_e32 v3, 1, v14
	v_lshl_or_b32 v2, v3, 6, v2
	v_lshl_add_u32 v2, v16, 1, v2
	v_mov_b32_e32 v3, v197
	v_lshl_add_u64 v[202:203], v[2:3], 0, s[14:15]
	v_lshlrev_b32_e32 v2, 14, v11
	v_and_b32_e32 v2, 0xffff8000, v2
	v_lshl_add_u32 v2, v12, 11, v2
	v_and_b32_e32 v3, 1, v11
	s_waitcnt vmcnt(6)
	v_lshl_or_b32 v2, v3, 6, v2
	s_cmpk_lt_u32 s8, 0x100
	v_lshl_add_u32 v2, v13, 1, v2
	v_mov_b32_e32 v3, v197
	s_sext_i32_i8 s71, s2
	s_cselect_b64 s[8:9], -1, 0
	s_ashr_i32 s65, s33, 31
	v_lshl_add_u64 v[204:205], v[2:3], 0, s[14:15]
	s_mov_b32 s34, 0
	v_mov_b64_e32 v[206:207], 0x200
	v_mov_b64_e32 v[208:209], 0x1ff
	v_add_u32_e32 v224, s10, v222
	v_add_u32_e32 v225, s12, v222
	v_add_u32_e32 v226, s3, v5
	v_mov_b32_e32 v227, 0x7f7f7f7f
	s_mov_b32 s10, 0x3a000000
	s_mov_b64 s[12:13], 0x80000
	s_mov_b32 s66, 0x80000
	s_mov_b64 s[14:15], 0x90000
	s_mov_b32 s67, 0x90000
	s_mov_b64 s[16:17], 0xa0000
	s_mov_b32 s68, 0xa0000
	s_mov_b64 s[18:19], 0xb0000
	s_mov_b32 s69, 0xb0000
	s_barrier
	s_branch .LBB0_2398

.LBB0_2409:
	s_waitcnt lgkmcnt(0)
	s_barrier
	s_setprio 1
	v_mfma_f32_16x16x128_f8f6f4 v[126:129], v[26:33], v[58:65], v[126:129]
	v_mfma_f32_16x16x128_f8f6f4 v[122:125], v[18:25], v[58:65], v[122:125]
	v_mfma_f32_16x16x128_f8f6f4 v[114:117], v[26:33], v[50:57], v[114:117]
	v_mfma_f32_16x16x128_f8f6f4 v[106:109], v[18:25], v[50:57], v[106:109]
	v_mfma_f32_16x16x128_f8f6f4 v[98:101], v[26:33], v[42:49], v[98:101]
	v_mfma_f32_16x16x128_f8f6f4 v[90:93], v[18:25], v[42:49], v[90:93]
	v_mfma_f32_16x16x128_f8f6f4 v[82:85], v[26:33], v[34:41], v[82:85]
	v_mfma_f32_16x16x128_f8f6f4 v[74:77], v[18:25], v[34:41], v[74:77]
	v_mfma_f32_16x16x128_f8f6f4 v[118:121], v[10:17], v[58:65], v[118:121]
	v_mfma_f32_16x16x128_f8f6f4 v[110:113], v[2:9], v[58:65], v[110:113]
	v_mfma_f32_16x16x128_f8f6f4 v[102:105], v[10:17], v[50:57], v[102:105]
	v_mfma_f32_16x16x128_f8f6f4 v[94:97], v[2:9], v[50:57], v[94:97]
	v_mfma_f32_16x16x128_f8f6f4 v[86:89], v[10:17], v[42:49], v[86:89]
	v_mfma_f32_16x16x128_f8f6f4 v[78:81], v[2:9], v[42:49], v[78:81]
	v_mfma_f32_16x16x128_f8f6f4 v[70:73], v[10:17], v[34:41], v[70:73]
	v_mfma_f32_16x16x128_f8f6f4 v[66:69], v[2:9], v[34:41], v[66:69]
	s_setprio 0
	s_barrier
	ds_read_b128 v[2:5], v253
	ds_read_b128 v[6:9], v253 offset:1024
	ds_read_b128 v[10:13], v253 offset:2048
	ds_read_b128 v[14:17], v253 offset:3072
	ds_read_b128 v[18:21], v254
	ds_read_b128 v[22:25], v254 offset:1024
	ds_read_b128 v[26:29], v254 offset:2048
	ds_read_b128 v[30:33], v254 offset:3072
	s_add_u32 s100, s40, 0x40000
	s_addc_u32 s101, s41, 0
	s_mov_b32 m0, s55
	ds_read_b128 v[34:37], v226 offset:32768
	ds_read_b128 v[38:41], v226 offset:33792
	ds_read_b128 v[42:45], v226 offset:34816
	ds_read_b128 v[46:49], v226 offset:35840
	ds_read_b128 v[50:53], v226 offset:36864
	ds_read_b128 v[54:57], v226 offset:37888
	ds_read_b128 v[58:61], v226 offset:38912
	ds_read_b128 v[62:65], v226 offset:39936
	global_load_lds_dwordx4 v194, s[100:101]
	s_mov_b32 m0, s56
	s_nop 0
	global_load_lds_dwordx4 v198, s[100:101]
	s_waitcnt lgkmcnt(0)
	s_barrier
	s_setprio 1
	v_mfma_f32_16x16x128_f8f6f4 v[190:193], v[2:9], v[34:41], v[190:193]
	v_mfma_f32_16x16x128_f8f6f4 v[186:189], v[10:17], v[34:41], v[186:189]
	v_mfma_f32_16x16x128_f8f6f4 v[178:181], v[2:9], v[42:49], v[178:181]
	v_mfma_f32_16x16x128_f8f6f4 v[170:173], v[10:17], v[42:49], v[170:173]
	v_mfma_f32_16x16x128_f8f6f4 v[162:165], v[2:9], v[50:57], v[162:165]
	v_mfma_f32_16x16x128_f8f6f4 v[154:157], v[10:17], v[50:57], v[154:157]
	v_mfma_f32_16x16x128_f8f6f4 v[146:149], v[2:9], v[58:65], v[146:149]
	v_mfma_f32_16x16x128_f8f6f4 v[138:141], v[10:17], v[58:65], v[138:141]
	v_mfma_f32_16x16x128_f8f6f4 v[182:185], v[18:25], v[34:41], v[182:185]
	v_mfma_f32_16x16x128_f8f6f4 v[174:177], v[26:33], v[34:41], v[174:177]
	v_mfma_f32_16x16x128_f8f6f4 v[166:169], v[18:25], v[42:49], v[166:169]
	v_mfma_f32_16x16x128_f8f6f4 v[158:161], v[26:33], v[42:49], v[158:161]
	v_mfma_f32_16x16x128_f8f6f4 v[150:153], v[18:25], v[50:57], v[150:153]
	v_mfma_f32_16x16x128_f8f6f4 v[142:145], v[26:33], v[50:57], v[142:145]
	v_mfma_f32_16x16x128_f8f6f4 v[134:137], v[18:25], v[58:65], v[134:137]
	v_mfma_f32_16x16x128_f8f6f4 v[130:133], v[26:33], v[58:65], v[130:133]
	s_setprio 0
	s_waitcnt vmcnt(8)
	s_barrier
	s_mov_b32 m0, s58
	ds_read_b128 v[34:37], v226 offset:49152
	ds_read_b128 v[38:41], v226 offset:50176
	ds_read_b128 v[42:45], v226 offset:51200
	ds_read_b128 v[46:49], v226 offset:52224
	ds_read_b128 v[50:53], v226 offset:53248
	ds_read_b128 v[54:57], v226 offset:54272
	ds_read_b128 v[58:61], v226 offset:55296
	ds_read_b128 v[62:65], v226 offset:56320
	s_add_u32 s98, s38, 0x80
	s_addc_u32 s99, s39, 0
	global_load_lds_dwordx4 v196, s[98:99]
	s_mov_b32 m0, s59
	s_nop 0
	global_load_lds_dwordx4 v200, s[98:99]
	s_mov_b32 m0, s63
	s_add_u32 s100, s78, 0x80
	s_addc_u32 s101, s79, 0
	global_load_lds_dwordx4 v196, s[100:101]
	s_mov_b32 m0, s64
	s_nop 0
	global_load_lds_dwordx4 v200, s[100:101]
	s_mov_b32 m0, s60
	s_add_u32 s98, s40, 0x80
	s_addc_u32 s99, s41, 0
	global_load_lds_dwordx4 v194, s[98:99]
	s_mov_b32 m0, s61
	s_nop 0
	global_load_lds_dwordx4 v198, s[98:99]
	s_waitcnt lgkmcnt(0)
	s_barrier
	s_setprio 1
	v_mfma_f32_16x16x128_f8f6f4 v[126:129], v[2:9], v[34:41], v[126:129]
	v_mfma_f32_16x16x128_f8f6f4 v[122:125], v[10:17], v[34:41], v[122:125]
	v_mfma_f32_16x16x128_f8f6f4 v[114:117], v[2:9], v[42:49], v[114:117]
	v_mfma_f32_16x16x128_f8f6f4 v[106:109], v[10:17], v[42:49], v[106:109]
	v_mfma_f32_16x16x128_f8f6f4 v[98:101], v[2:9], v[50:57], v[98:101]
	v_mfma_f32_16x16x128_f8f6f4 v[90:93], v[10:17], v[50:57], v[90:93]
	v_mfma_f32_16x16x128_f8f6f4 v[82:85], v[2:9], v[58:65], v[82:85]
	v_mfma_f32_16x16x128_f8f6f4 v[74:77], v[10:17], v[58:65], v[74:77]
	v_mfma_f32_16x16x128_f8f6f4 v[118:121], v[18:25], v[34:41], v[118:121]
	v_mfma_f32_16x16x128_f8f6f4 v[110:113], v[26:33], v[34:41], v[110:113]
	v_mfma_f32_16x16x128_f8f6f4 v[102:105], v[18:25], v[42:49], v[102:105]
	v_mfma_f32_16x16x128_f8f6f4 v[94:97], v[26:33], v[42:49], v[94:97]
	v_mfma_f32_16x16x128_f8f6f4 v[86:89], v[18:25], v[50:57], v[86:89]
	v_mfma_f32_16x16x128_f8f6f4 v[78:81], v[26:33], v[50:57], v[78:81]
	v_mfma_f32_16x16x128_f8f6f4 v[70:73], v[18:25], v[58:65], v[70:73]
	v_mfma_f32_16x16x128_f8f6f4 v[66:69], v[26:33], v[58:65], v[66:69]
	s_setprio 0
	s_waitcnt vmcnt(8)
	s_barrier
	s_add_i32 s76, s76, 2
	s_add_u32 s36, s36, 0x100
	s_addc_u32 s37, s37, 0
	s_cmp_gt_u32 s76, 13
	s_cbranch_scc1 .LBB0_2417

.LBB0_2413:
	s_add_u32 s38, s30, s36
	s_addc_u32 s39, s31, s37
	s_add_u32 s38, s38, 0x100
	s_addc_u32 s39, s39, 0
	s_add_u32 s77, s74, s36
	s_addc_u32 s78, s75, s37
	s_waitcnt lgkmcnt(0)
	s_cmpk_eq_i32 s36, 0x700
	s_cselect_b32 s41, s21, s39
	s_cselect_b32 s40, s72, s38
	s_cselect_b32 s39, s23, s78
	s_cselect_b32 s38, s73, s77
	s_barrier
	s_setprio 1
	s_waitcnt lgkmcnt(0)
	v_mfma_f32_16x16x128_f8f6f4 v[190:193], v[26:33], v[58:65], v[190:193]
	v_mfma_f32_16x16x128_f8f6f4 v[186:189], v[18:25], v[58:65], v[186:189]
	v_mfma_f32_16x16x128_f8f6f4 v[178:181], v[26:33], v[50:57], v[178:181]
	v_mfma_f32_16x16x128_f8f6f4 v[170:173], v[18:25], v[50:57], v[170:173]
	v_mfma_f32_16x16x128_f8f6f4 v[162:165], v[26:33], v[42:49], v[162:165]
	v_mfma_f32_16x16x128_f8f6f4 v[154:157], v[18:25], v[42:49], v[154:157]
	v_mfma_f32_16x16x128_f8f6f4 v[146:149], v[26:33], v[34:41], v[146:149]
	v_mfma_f32_16x16x128_f8f6f4 v[138:141], v[18:25], v[34:41], v[138:141]
	v_mfma_f32_16x16x128_f8f6f4 v[182:185], v[10:17], v[58:65], v[182:185]
	v_mfma_f32_16x16x128_f8f6f4 v[174:177], v[2:9], v[58:65], v[174:177]
	v_mfma_f32_16x16x128_f8f6f4 v[166:169], v[10:17], v[50:57], v[166:169]
	v_mfma_f32_16x16x128_f8f6f4 v[158:161], v[2:9], v[50:57], v[158:161]
	v_mfma_f32_16x16x128_f8f6f4 v[150:153], v[10:17], v[42:49], v[150:153]
	v_mfma_f32_16x16x128_f8f6f4 v[142:145], v[2:9], v[42:49], v[142:145]
	v_mfma_f32_16x16x128_f8f6f4 v[134:137], v[10:17], v[34:41], v[134:137]
	v_mfma_f32_16x16x128_f8f6f4 v[130:133], v[2:9], v[34:41], v[130:133]
	s_setprio 0
	s_barrier
	s_mov_b32 m0, s29
	s_add_u32 s78, s38, 0x40000
	ds_read_b128 v[58:61], v226 offset:16384
	ds_read_b128 v[62:65], v226 offset:17408
	ds_read_b128 v[50:53], v226 offset:18432
	ds_read_b128 v[54:57], v226 offset:19456
	ds_read_b128 v[42:45], v226 offset:20480
	ds_read_b128 v[46:49], v226 offset:21504
	ds_read_b128 v[34:37], v226 offset:22528
	ds_read_b128 v[38:41], v226 offset:23552
	global_load_lds_dwordx4 v196, s[38:39]
	s_mov_b32 m0, s50
	s_addc_u32 s79, s39, 0
	global_load_lds_dwordx4 v200, s[38:39]
	s_mov_b32 m0, s51
	s_nop 0
	global_load_lds_dwordx4 v196, s[78:79]
	s_mov_b32 m0, s52
	s_andn2_b64 vcc, exec, s[42:43]
	global_load_lds_dwordx4 v200, s[78:79]
	s_mov_b32 m0, s53
	s_nop 0
	global_load_lds_dwordx4 v194, s[40:41]
	s_mov_b32 m0, s54
	s_nop 0
	global_load_lds_dwordx4 v198, s[40:41]
	s_cbranch_vccnz .LBB0_2416
	s_waitcnt vmcnt(24)
	s_cbranch_execnz .LBB0_2409
	s_branch .LBB0_2408

.LBB0_2549:
	s_add_u32 s16, s3, 0x30200000
	s_addc_u32 s17, s4, 0
	s_add_u32 s18, s15, 0x10800
	s_addc_u32 s19, s31, 0
	s_add_u32 s20, s5, 0x5800
	s_addc_u32 s21, s6, 0
	s_add_u32 s22, s3, 0x17600000
	s_addc_u32 s23, s4, 0
	s_add_u32 s72, s3, 0x18600000
	s_addc_u32 s73, s4, 0
	s_lshl_b32 s4, s8, 5
	s_add_i32 s74, s14, 0x18000
	s_and_b32 s38, s4, 0x60
	s_add_i32 s75, s74, s7
	s_mov_b64 s[24:25], 0x80
	s_lshl_b32 s3, s63, 6
	s_lshl_b32 s6, s63, 13
	s_lshl_b32 s8, s38, 7
	v_lshl_add_u64 v[8:9], v[8:9], 0, s[24:25]
	s_mov_b32 m0, s75
	s_add_i32 s76, s75, 0x2000
	s_add_i32 s77, s68, 0x8000
	s_add_i32 s78, s68, 0xa000
	s_waitcnt vmcnt(2)
	s_barrier
	global_load_lds_dwordx4 v[8:9], off
	v_lshl_add_u64 v[6:7], v[6:7], 0, s[24:25]
	s_mov_b32 m0, s76
	s_add_u32 s4, s50, 0x80080
	global_load_lds_dwordx4 v[6:7], off
	v_lshl_add_u64 v[2:3], v[2:3], 0, s[24:25]
	s_mov_b32 m0, s77
	s_addc_u32 s5, s51, 0
	s_add_i32 s79, s14, 0x1c000
	global_load_lds_dwordx4 v[2:3], off
	v_lshl_add_u64 v[2:3], v[4:5], 0, s[24:25]
	s_mov_b32 m0, s78
	s_add_i32 s80, s79, s7
	global_load_lds_dwordx4 v[2:3], off
	v_lshl_add_u64 v[2:3], s[4:5], 0, v[196:197]
	s_mov_b32 m0, s80
	s_add_i32 s81, s80, 0x2000
	global_load_lds_dwordx4 v[2:3], off
	v_lshl_add_u64 v[2:3], s[4:5], 0, v[200:201]
	s_mov_b32 m0, s81
	v_and_b32_e32 v202, 15, v1
	global_load_lds_dwordx4 v[2:3], off
	v_lshrrev_b32_e32 v2, 1, v1
	v_and_b32_e32 v2, 24, v2
	v_lshlrev_b32_e32 v3, 1, v2
	v_lshlrev_b32_e32 v1, 2, v1
	v_or_b32_e32 v203, s38, v2
	v_lshlrev_b32_e32 v2, 15, v13
	v_lshl_or_b32 v3, v202, 6, v3
	v_and_b32_e32 v1, 32, v1
	v_and_b32_e32 v2, 0xffff0000, v2
	v_bitop3_b32 v4, v3, s6, v1 bitop3:0xde
	v_bitop3_b32 v1, v3, s8, v1 bitop3:0xde
	v_add_u32_e32 v253, s74, v1
	v_add_u32_e32 v254, s79, v1
	v_lshl_add_u32 v2, v14, 12, v2
	v_and_b32_e32 v3, 1, v13
	v_lshl_or_b32 v2, v3, 6, v2
	s_mov_b64 s[36:37], 0x80080
	v_lshl_add_u32 v2, v15, 1, v2
	v_mov_b32_e32 v3, v197
	s_cmpk_lt_u32 s2, 0x100
	v_lshl_add_u64 v[208:209], v[2:3], 0, s[36:37]
	v_lshlrev_b32_e32 v2, 15, v10
	s_cselect_b64 s[26:27], -1, 0
	s_ashr_i32 s2, s3, 31
	s_ashr_i32 s82, s33, 31
	s_ashr_i32 s83, s58, 31
	v_and_b32_e32 v2, 0xffff0000, v2
	s_add_u32 s28, s15, 0x16000
	v_lshl_add_u32 v2, v11, 12, v2
	v_and_b32_e32 v3, 1, v10
	s_waitcnt vmcnt(6)
	s_addc_u32 s29, s31, 0
	v_lshl_or_b32 v2, v3, 6, v2
	s_add_u32 s30, s15, 0x1b800
	v_lshl_add_u32 v2, v12, 1, v2
	v_mov_b32_e32 v3, v197
	v_or_b32_e32 v204, s3, v202
	v_mov_b32_e32 v205, s2
	v_cmp_eq_u32_e64 s[2:3], 15, v202
	s_mov_b32 s48, 0
	v_cmp_eq_u32_e64 s[4:5], 0, v202
	v_cmp_ne_u32_e64 s[6:7], 15, v202
	v_cmp_ne_u32_e64 s[8:9], 0, v202
	v_cmp_gt_u32_e64 s[10:11], 2, v202
	v_cmp_lt_u32_e64 s[12:13], 13, v202
	v_add_u32_e32 v206, -12, v202
	v_mov_b32_e32 v207, v197
	s_addc_u32 s31, s31, 0
	v_lshl_add_u64 v[210:211], v[2:3], 0, s[36:37]
	v_mov_b64_e32 v[212:213], 0xb00
	v_mov_b64_e32 v[214:215], 0xaff
	s_movk_i32 s84, 0x161
	v_add_u32_e32 v228, s34, v1
	v_add_u32_e32 v229, s35, v1
	v_add_u32_e32 v231, s14, v4
	s_movk_i32 s85, 0x2c00
	s_mov_b32 s86, 0x2c000
	s_mov_b32 s87, 0x58000
	s_mov_b32 s88, 0x18c000
	s_mov_b32 s89, 0x1b8000
	v_mov_b32_e32 v232, 0x2c00
	s_barrier
	s_branch .LBB0_2552

.LBB0_2723:
	s_add_u32 s6, s6, 0xe600000
	s_addc_u32 s7, s7, 0
	s_lshl_b32 s8, s8, 5
	s_add_i32 s48, s12, 0x18000
	s_and_b32 s16, s8, 0x60
	s_add_i32 s49, s48, s11
	s_mov_b64 s[8:9], 0x80
	s_lshl_b32 s13, s0, 13
	s_lshl_b32 s17, s16, 7
	v_lshl_add_u64 v[8:9], v[8:9], 0, s[8:9]
	s_mov_b32 m0, s49
	s_add_i32 s50, s49, 0x2000
	s_add_i32 s51, s44, 0x8000
	s_add_i32 s52, s44, 0xa000
	s_waitcnt vmcnt(2)
	s_barrier
	global_load_lds_dwordx4 v[8:9], off
	v_lshl_add_u64 v[6:7], v[6:7], 0, s[8:9]
	s_mov_b32 m0, s50
	s_add_u32 s14, s26, 0x160080
	global_load_lds_dwordx4 v[6:7], off
	v_lshl_add_u64 v[2:3], v[2:3], 0, s[8:9]
	s_mov_b32 m0, s51
	s_addc_u32 s15, s27, 0
	s_add_i32 s53, s12, 0x1c000
	global_load_lds_dwordx4 v[2:3], off
	v_lshl_add_u64 v[2:3], v[4:5], 0, s[8:9]
	s_mov_b32 m0, s52
	s_add_i32 s54, s53, s11
	global_load_lds_dwordx4 v[2:3], off
	v_lshl_add_u64 v[2:3], s[14:15], 0, v[196:197]
	s_mov_b32 m0, s54
	s_add_i32 s55, s54, 0x2000
	global_load_lds_dwordx4 v[2:3], off
	v_lshl_add_u64 v[2:3], s[14:15], 0, v[200:201]
	s_mov_b32 m0, s55
	s_mov_b64 s[14:15], 0x160080
	global_load_lds_dwordx4 v[2:3], off
	v_lshrrev_b32_e32 v3, 1, v10
	v_and_b32_e32 v3, 24, v3
	v_and_b32_e32 v2, 15, v10
	v_lshlrev_b32_e32 v4, 1, v3
	v_lshl_or_b32 v1, s0, 6, v2
	v_lshl_or_b32 v2, v2, 6, v4
	v_lshlrev_b32_e32 v4, 2, v10
	v_and_b32_e32 v4, 32, v4
	v_bitop3_b32 v5, v2, s13, v4 bitop3:0xde
	v_bitop3_b32 v222, v2, s17, v4 bitop3:0xde
	v_add_u32_e32 v253, s48, v222
	v_add_u32_e32 v254, s53, v222
	v_or_b32_e32 v223, s16, v3
	v_lshrrev_b32_e32 v3, 1, v15
	v_mul_lo_u32 v2, v17, s1
	s_mov_b32 s0, 0x16000
	v_mad_u64_u32 v[2:3], s[16:17], v3, s0, v[2:3]
	v_or_b32_e32 v2, v2, v16
	v_add_lshl_u32 v2, v2, v18, 1
	v_mov_b32_e32 v3, v197
	v_lshl_add_u64 v[202:203], v[2:3], 0, s[14:15]
	v_lshrrev_b32_e32 v3, 1, v11
	v_mul_lo_u32 v2, v12, s1
	v_mad_u64_u32 v[2:3], s[0:1], v3, s0, v[2:3]
	s_waitcnt vmcnt(6)
	v_or_b32_e32 v2, v2, v13
	s_cmpk_lt_u32 s10, 0x100
	v_add_lshl_u32 v2, v2, v14, 1
	v_mov_b32_e32 v3, v197
	s_cselect_b64 s[10:11], -1, 0
	s_ashr_i32 s56, s33, 31
	s_ashr_i32 s57, s72, 31
	v_lshl_add_u64 v[204:205], v[2:3], 0, s[14:15]
	s_mov_b32 s24, 0
	v_mov_b64_e32 v[206:207], 0x200
	v_mov_b64_e32 v[208:209], 0x1ff
	v_add_u32_e32 v224, s2, v222
	v_add_u32_e32 v225, s3, v222
	v_add_u32_e32 v226, s12, v5
	s_mov_b64 s[12:13], 0x80000
	s_mov_b32 s58, 0x80000
	s_mov_b64 s[14:15], 0x90000
	s_mov_b32 s59, 0x90000
	s_mov_b64 s[16:17], 0xa0000
	s_mov_b32 s60, 0xa0000
	s_mov_b64 s[18:19], 0xb0000
	s_mov_b32 s61, 0xb0000
	s_barrier
	s_waitcnt vmcnt(0)
	s_branch .LBB0_2726

.LBB0_2741:
	s_waitcnt lgkmcnt(0)
	s_barrier
	s_setprio 1
	v_mfma_f32_16x16x32_bf16 v[62:65], v[146:149], v[186:189], v[62:65]
	v_mfma_f32_16x16x32_bf16 v[58:61], v[154:157], v[186:189], v[58:61]
	v_mfma_f32_16x16x32_bf16 v[54:57], v[146:149], v[178:181], v[54:57]
	v_mfma_f32_16x16x32_bf16 v[46:49], v[154:157], v[178:181], v[46:49]
	v_mfma_f32_16x16x32_bf16 v[38:41], v[146:149], v[170:173], v[38:41]
	v_mfma_f32_16x16x32_bf16 v[30:33], v[154:157], v[170:173], v[30:33]
	v_mfma_f32_16x16x32_bf16 v[22:25], v[146:149], v[162:165], v[22:25]
	v_mfma_f32_16x16x32_bf16 v[14:17], v[154:157], v[162:165], v[14:17]
	v_mfma_f32_16x16x32_bf16 v[62:65], v[150:153], v[190:193], v[62:65]
	v_mfma_f32_16x16x32_bf16 v[58:61], v[158:161], v[190:193], v[58:61]
	v_mfma_f32_16x16x32_bf16 v[54:57], v[150:153], v[182:185], v[54:57]
	v_mfma_f32_16x16x32_bf16 v[46:49], v[158:161], v[182:185], v[46:49]
	v_mfma_f32_16x16x32_bf16 v[38:41], v[150:153], v[174:177], v[38:41]
	v_mfma_f32_16x16x32_bf16 v[30:33], v[158:161], v[174:177], v[30:33]
	v_mfma_f32_16x16x32_bf16 v[22:25], v[150:153], v[166:169], v[22:25]
	v_mfma_f32_16x16x32_bf16 v[14:17], v[158:161], v[166:169], v[14:17]
	v_mfma_f32_16x16x32_bf16 v[50:53], v[130:133], v[186:189], v[50:53]
	v_mfma_f32_16x16x32_bf16 v[42:45], v[138:141], v[186:189], v[42:45]
	v_mfma_f32_16x16x32_bf16 v[34:37], v[130:133], v[178:181], v[34:37]
	v_mfma_f32_16x16x32_bf16 v[26:29], v[138:141], v[178:181], v[26:29]
	v_mfma_f32_16x16x32_bf16 v[18:21], v[130:133], v[170:173], v[18:21]
	v_mfma_f32_16x16x32_bf16 v[10:13], v[138:141], v[170:173], v[10:13]
	v_mfma_f32_16x16x32_bf16 v[6:9], v[130:133], v[162:165], v[6:9]
	v_mfma_f32_16x16x32_bf16 v[2:5], v[138:141], v[162:165], v[2:5]
	v_mfma_f32_16x16x32_bf16 v[50:53], v[134:137], v[190:193], v[50:53]
	v_mfma_f32_16x16x32_bf16 v[42:45], v[142:145], v[190:193], v[42:45]
	v_mfma_f32_16x16x32_bf16 v[34:37], v[134:137], v[182:185], v[34:37]
	v_mfma_f32_16x16x32_bf16 v[26:29], v[142:145], v[182:185], v[26:29]
	v_mfma_f32_16x16x32_bf16 v[18:21], v[134:137], v[174:177], v[18:21]
	v_mfma_f32_16x16x32_bf16 v[10:13], v[142:145], v[174:177], v[10:13]
	v_mfma_f32_16x16x32_bf16 v[6:9], v[134:137], v[166:169], v[6:9]
	v_mfma_f32_16x16x32_bf16 v[2:5], v[142:145], v[166:169], v[2:5]
	s_setprio 0
	s_barrier
	ds_read_b128 v[130:133], v253
	ds_read_b128 v[134:137], v253 offset:1024
	ds_read_b128 v[138:141], v253 offset:2048
	ds_read_b128 v[142:145], v253 offset:3072
	ds_read_b128 v[146:149], v254
	ds_read_b128 v[150:153], v254 offset:1024
	ds_read_b128 v[154:157], v254 offset:2048
	ds_read_b128 v[158:161], v254 offset:3072
	s_add_u32 s100, s30, 0x160000
	s_addc_u32 s101, s31, 0
	s_mov_b32 m0, s46
	ds_read_b128 v[162:165], v226 offset:32768
	ds_read_b128 v[166:169], v226 offset:33792
	ds_read_b128 v[170:173], v226 offset:34816
	ds_read_b128 v[174:177], v226 offset:35840
	ds_read_b128 v[178:181], v226 offset:36864
	ds_read_b128 v[182:185], v226 offset:37888
	ds_read_b128 v[186:189], v226 offset:38912
	ds_read_b128 v[190:193], v226 offset:39936
	global_load_lds_dwordx4 v194, s[100:101]
	s_mov_b32 m0, s47
	s_nop 0
	global_load_lds_dwordx4 v198, s[100:101]
	s_waitcnt lgkmcnt(0)
	s_barrier
	s_setprio 1
	v_mfma_f32_16x16x32_bf16 v[126:129], v[130:133], v[162:165], v[126:129]
	v_mfma_f32_16x16x32_bf16 v[122:125], v[138:141], v[162:165], v[122:125]
	v_mfma_f32_16x16x32_bf16 v[118:121], v[130:133], v[170:173], v[118:121]
	v_mfma_f32_16x16x32_bf16 v[110:113], v[138:141], v[170:173], v[110:113]
	v_mfma_f32_16x16x32_bf16 v[102:105], v[130:133], v[178:181], v[102:105]
	v_mfma_f32_16x16x32_bf16 v[94:97], v[138:141], v[178:181], v[94:97]
	v_mfma_f32_16x16x32_bf16 v[86:89], v[130:133], v[186:189], v[86:89]
	v_mfma_f32_16x16x32_bf16 v[78:81], v[138:141], v[186:189], v[78:81]
	v_mfma_f32_16x16x32_bf16 v[126:129], v[134:137], v[166:169], v[126:129]
	v_mfma_f32_16x16x32_bf16 v[122:125], v[142:145], v[166:169], v[122:125]
	v_mfma_f32_16x16x32_bf16 v[118:121], v[134:137], v[174:177], v[118:121]
	v_mfma_f32_16x16x32_bf16 v[110:113], v[142:145], v[174:177], v[110:113]
	v_mfma_f32_16x16x32_bf16 v[102:105], v[134:137], v[182:185], v[102:105]
	v_mfma_f32_16x16x32_bf16 v[94:97], v[142:145], v[182:185], v[94:97]
	v_mfma_f32_16x16x32_bf16 v[86:89], v[134:137], v[190:193], v[86:89]
	v_mfma_f32_16x16x32_bf16 v[78:81], v[142:145], v[190:193], v[78:81]
	v_mfma_f32_16x16x32_bf16 v[114:117], v[146:149], v[162:165], v[114:117]
	v_mfma_f32_16x16x32_bf16 v[106:109], v[154:157], v[162:165], v[106:109]
	v_mfma_f32_16x16x32_bf16 v[98:101], v[146:149], v[170:173], v[98:101]
	v_mfma_f32_16x16x32_bf16 v[90:93], v[154:157], v[170:173], v[90:93]
	v_mfma_f32_16x16x32_bf16 v[82:85], v[146:149], v[178:181], v[82:85]
	v_mfma_f32_16x16x32_bf16 v[74:77], v[154:157], v[178:181], v[74:77]
	v_mfma_f32_16x16x32_bf16 v[70:73], v[146:149], v[186:189], v[70:73]
	v_mfma_f32_16x16x32_bf16 v[66:69], v[154:157], v[186:189], v[66:69]
	v_mfma_f32_16x16x32_bf16 v[114:117], v[150:153], v[166:169], v[114:117]
	v_mfma_f32_16x16x32_bf16 v[106:109], v[158:161], v[166:169], v[106:109]
	v_mfma_f32_16x16x32_bf16 v[98:101], v[150:153], v[174:177], v[98:101]
	v_mfma_f32_16x16x32_bf16 v[90:93], v[158:161], v[174:177], v[90:93]
	v_mfma_f32_16x16x32_bf16 v[82:85], v[150:153], v[182:185], v[82:85]
	v_mfma_f32_16x16x32_bf16 v[74:77], v[158:161], v[182:185], v[74:77]
	v_mfma_f32_16x16x32_bf16 v[70:73], v[150:153], v[190:193], v[70:73]
	v_mfma_f32_16x16x32_bf16 v[66:69], v[158:161], v[190:193], v[66:69]
	s_setprio 0
	s_waitcnt vmcnt(8)
	s_barrier
	s_mov_b32 m0, s49
	ds_read_b128 v[162:165], v226 offset:49152
	ds_read_b128 v[166:169], v226 offset:50176
	ds_read_b128 v[170:173], v226 offset:51200
	ds_read_b128 v[174:177], v226 offset:52224
	ds_read_b128 v[178:181], v226 offset:53248
	ds_read_b128 v[182:185], v226 offset:54272
	ds_read_b128 v[186:189], v226 offset:55296
	ds_read_b128 v[190:193], v226 offset:56320
	s_add_u32 s98, s28, 0x80
	s_addc_u32 s99, s29, 0
	global_load_lds_dwordx4 v196, s[98:99]
	s_mov_b32 m0, s50
	s_nop 0
	global_load_lds_dwordx4 v200, s[98:99]
	s_mov_b32 m0, s54
	s_add_u32 s100, s70, 0x80
	s_addc_u32 s101, s71, 0
	global_load_lds_dwordx4 v196, s[100:101]
	s_mov_b32 m0, s55
	s_nop 0
	global_load_lds_dwordx4 v200, s[100:101]
	s_mov_b32 m0, s51
	s_add_u32 s98, s30, 0x80
	s_addc_u32 s99, s31, 0
	global_load_lds_dwordx4 v194, s[98:99]
	s_mov_b32 m0, s52
	s_nop 0
	global_load_lds_dwordx4 v198, s[98:99]
	s_waitcnt lgkmcnt(0)
	s_barrier
	s_setprio 1
	v_mfma_f32_16x16x32_bf16 v[62:65], v[130:133], v[162:165], v[62:65]
	v_mfma_f32_16x16x32_bf16 v[58:61], v[138:141], v[162:165], v[58:61]
	v_mfma_f32_16x16x32_bf16 v[54:57], v[130:133], v[170:173], v[54:57]
	v_mfma_f32_16x16x32_bf16 v[46:49], v[138:141], v[170:173], v[46:49]
	v_mfma_f32_16x16x32_bf16 v[38:41], v[130:133], v[178:181], v[38:41]
	v_mfma_f32_16x16x32_bf16 v[30:33], v[138:141], v[178:181], v[30:33]
	v_mfma_f32_16x16x32_bf16 v[22:25], v[130:133], v[186:189], v[22:25]
	v_mfma_f32_16x16x32_bf16 v[14:17], v[138:141], v[186:189], v[14:17]
	v_mfma_f32_16x16x32_bf16 v[62:65], v[134:137], v[166:169], v[62:65]
	v_mfma_f32_16x16x32_bf16 v[58:61], v[142:145], v[166:169], v[58:61]
	v_mfma_f32_16x16x32_bf16 v[54:57], v[134:137], v[174:177], v[54:57]
	v_mfma_f32_16x16x32_bf16 v[46:49], v[142:145], v[174:177], v[46:49]
	v_mfma_f32_16x16x32_bf16 v[38:41], v[134:137], v[182:185], v[38:41]
	v_mfma_f32_16x16x32_bf16 v[30:33], v[142:145], v[182:185], v[30:33]
	v_mfma_f32_16x16x32_bf16 v[22:25], v[134:137], v[190:193], v[22:25]
	v_mfma_f32_16x16x32_bf16 v[14:17], v[142:145], v[190:193], v[14:17]
	v_mfma_f32_16x16x32_bf16 v[50:53], v[146:149], v[162:165], v[50:53]
	v_mfma_f32_16x16x32_bf16 v[42:45], v[154:157], v[162:165], v[42:45]
	v_mfma_f32_16x16x32_bf16 v[34:37], v[146:149], v[170:173], v[34:37]
	v_mfma_f32_16x16x32_bf16 v[26:29], v[154:157], v[170:173], v[26:29]
	v_mfma_f32_16x16x32_bf16 v[18:21], v[146:149], v[178:181], v[18:21]
	v_mfma_f32_16x16x32_bf16 v[10:13], v[154:157], v[178:181], v[10:13]
	v_mfma_f32_16x16x32_bf16 v[6:9], v[146:149], v[186:189], v[6:9]
	v_mfma_f32_16x16x32_bf16 v[2:5], v[154:157], v[186:189], v[2:5]
	v_mfma_f32_16x16x32_bf16 v[50:53], v[150:153], v[166:169], v[50:53]
	v_mfma_f32_16x16x32_bf16 v[42:45], v[158:161], v[166:169], v[42:45]
	v_mfma_f32_16x16x32_bf16 v[34:37], v[150:153], v[174:177], v[34:37]
	v_mfma_f32_16x16x32_bf16 v[26:29], v[158:161], v[174:177], v[26:29]
	v_mfma_f32_16x16x32_bf16 v[18:21], v[150:153], v[182:185], v[18:21]
	v_mfma_f32_16x16x32_bf16 v[10:13], v[158:161], v[182:185], v[10:13]
	v_mfma_f32_16x16x32_bf16 v[6:9], v[150:153], v[190:193], v[6:9]
	v_mfma_f32_16x16x32_bf16 v[2:5], v[158:161], v[190:193], v[2:5]
	s_setprio 0
	s_waitcnt vmcnt(8)
	s_barrier
	s_add_i32 s69, s69, 2
	s_add_u32 s26, s26, 0x100
	s_addc_u32 s27, s27, 0
	s_cmpk_gt_u32 s69, 0x55
	s_cbranch_scc1 .LBB0_2749

.LBB0_2745:
	s_add_u32 s28, s22, s26
	s_addc_u32 s29, s23, s27
	s_add_u32 s28, s28, 0x100
	s_addc_u32 s29, s29, 0
	s_add_u32 s70, s67, s26
	s_addc_u32 s71, s68, s27
	s_waitcnt lgkmcnt(0)
	s_cmpk_eq_i32 s26, 0x2b00
	s_cselect_b32 s31, s1, s29
	s_cselect_b32 s30, s0, s28
	s_cselect_b32 s29, s21, s71
	s_cselect_b32 s28, s20, s70
	s_barrier
	s_setprio 1
	s_waitcnt lgkmcnt(0)
	v_mfma_f32_16x16x32_bf16 v[126:129], v[146:149], v[186:189], v[126:129]
	v_mfma_f32_16x16x32_bf16 v[122:125], v[154:157], v[186:189], v[122:125]
	v_mfma_f32_16x16x32_bf16 v[118:121], v[146:149], v[178:181], v[118:121]
	v_mfma_f32_16x16x32_bf16 v[110:113], v[154:157], v[178:181], v[110:113]
	v_mfma_f32_16x16x32_bf16 v[102:105], v[146:149], v[170:173], v[102:105]
	v_mfma_f32_16x16x32_bf16 v[94:97], v[154:157], v[170:173], v[94:97]
	v_mfma_f32_16x16x32_bf16 v[86:89], v[146:149], v[162:165], v[86:89]
	v_mfma_f32_16x16x32_bf16 v[78:81], v[154:157], v[162:165], v[78:81]
	v_mfma_f32_16x16x32_bf16 v[126:129], v[150:153], v[190:193], v[126:129]
	v_mfma_f32_16x16x32_bf16 v[122:125], v[158:161], v[190:193], v[122:125]
	v_mfma_f32_16x16x32_bf16 v[118:121], v[150:153], v[182:185], v[118:121]
	v_mfma_f32_16x16x32_bf16 v[110:113], v[158:161], v[182:185], v[110:113]
	v_mfma_f32_16x16x32_bf16 v[102:105], v[150:153], v[174:177], v[102:105]
	v_mfma_f32_16x16x32_bf16 v[94:97], v[158:161], v[174:177], v[94:97]
	v_mfma_f32_16x16x32_bf16 v[86:89], v[150:153], v[166:169], v[86:89]
	v_mfma_f32_16x16x32_bf16 v[78:81], v[158:161], v[166:169], v[78:81]
	v_mfma_f32_16x16x32_bf16 v[114:117], v[130:133], v[186:189], v[114:117]
	v_mfma_f32_16x16x32_bf16 v[106:109], v[138:141], v[186:189], v[106:109]
	v_mfma_f32_16x16x32_bf16 v[98:101], v[130:133], v[178:181], v[98:101]
	v_mfma_f32_16x16x32_bf16 v[90:93], v[138:141], v[178:181], v[90:93]
	v_mfma_f32_16x16x32_bf16 v[82:85], v[130:133], v[170:173], v[82:85]
	v_mfma_f32_16x16x32_bf16 v[74:77], v[138:141], v[170:173], v[74:77]
	v_mfma_f32_16x16x32_bf16 v[70:73], v[130:133], v[162:165], v[70:73]
	v_mfma_f32_16x16x32_bf16 v[66:69], v[138:141], v[162:165], v[66:69]
	v_mfma_f32_16x16x32_bf16 v[114:117], v[134:137], v[190:193], v[114:117]
	v_mfma_f32_16x16x32_bf16 v[106:109], v[142:145], v[190:193], v[106:109]
	v_mfma_f32_16x16x32_bf16 v[98:101], v[134:137], v[182:185], v[98:101]
	v_mfma_f32_16x16x32_bf16 v[90:93], v[142:145], v[182:185], v[90:93]
	v_mfma_f32_16x16x32_bf16 v[82:85], v[134:137], v[174:177], v[82:85]
	v_mfma_f32_16x16x32_bf16 v[74:77], v[142:145], v[174:177], v[74:77]
	v_mfma_f32_16x16x32_bf16 v[70:73], v[134:137], v[166:169], v[70:73]
	v_mfma_f32_16x16x32_bf16 v[66:69], v[142:145], v[166:169], v[66:69]
	s_setprio 0
	s_barrier
	s_mov_b32 m0, s40
	s_add_u32 s70, s28, 0x160000
	ds_read_b128 v[186:189], v226 offset:16384
	ds_read_b128 v[190:193], v226 offset:17408
	ds_read_b128 v[178:181], v226 offset:18432
	ds_read_b128 v[182:185], v226 offset:19456
	ds_read_b128 v[170:173], v226 offset:20480
	ds_read_b128 v[174:177], v226 offset:21504
	ds_read_b128 v[162:165], v226 offset:22528
	ds_read_b128 v[166:169], v226 offset:23552
	global_load_lds_dwordx4 v196, s[28:29]
	s_mov_b32 m0, s41
	s_addc_u32 s71, s29, 0
	global_load_lds_dwordx4 v200, s[28:29]
	s_mov_b32 m0, s42
	s_nop 0
	global_load_lds_dwordx4 v196, s[70:71]
	s_mov_b32 m0, s43
	s_andn2_b64 vcc, exec, s[34:35]
	global_load_lds_dwordx4 v200, s[70:71]
	s_mov_b32 m0, s44
	s_nop 0
	global_load_lds_dwordx4 v194, s[30:31]
	s_mov_b32 m0, s45
	s_nop 0
	global_load_lds_dwordx4 v198, s[30:31]
	s_cbranch_vccnz .LBB0_2748
	s_waitcnt vmcnt(24)
	s_cbranch_execnz .LBB0_2741
	s_branch .LBB0_2740
